# P5 per-head query epilogue: norm partials and rope frequencies loaded once up front, all bf16 store pairs merged into 16-byte stores
# baseline (speedup 1.0000x reference)
.LBB0_620:
	v_and_b32_e32 v226, 16, v0
	v_lshrrev_b32_e32 v227, 1, v226
	v_add_u32_e32 v226, v226, v227
	v_mov_b32_e32 v227, 0
	v_lshl_add_u32 v146, s6, 8, v1
	v_ashrrev_i32_e32 v147, 31, v146
	v_lshlrev_b64 v[142:143], 5, v[146:147]
	v_lshl_add_u64 v[142:143], s[10:11], 0, v[142:143]
	global_load_dwordx4 v[162:165], v[142:143], off
	global_load_dwordx4 v[182:185], v[142:143], off offset:512
	global_load_dwordx4 v[186:189], v[142:143], off offset:1024
	global_load_dwordx4 v[190:193], v[142:143], off offset:1536
	v_add_co_u32_e32 v218, vcc, 0x1000, v142
	s_nop 1
	v_addc_co_u32_e32 v219, vcc, 0, v143, vcc
	global_load_dwordx4 v[194:197], v[218:219], off
	global_load_dwordx4 v[198:201], v[218:219], off offset:512
	global_load_dwordx4 v[202:205], v[218:219], off offset:1024
	global_load_dwordx4 v[206:209], v[218:219], off offset:1536
	global_load_dwordx4 v[210:213], v[138:139], off
	s_cmp_gt_i32 s8, 1
	s_cselect_b64 s[38:39], -1, 0
	s_mov_b64 s[6:7], -1
	v_lshlrev_b32_e32 v134, 1, v136
	v_lshlrev_b64 v[150:151], 3, v[146:147]
	s_and_b64 vcc, exec, s[38:39]
	s_waitcnt vmcnt(0)
	v_add_f32_e32 v142, v162, v163
	v_add_f32_e32 v143, v164, v165
	v_add_f32_e32 v142, v142, v143
	v_fmamk_f32 v142, v142, 0x3b800000, v158
	v_rsq_f32_e32 v142, v142
	s_nop 0
	v_mul_f32_e32 v148, 0x3e16c740, v142
	s_cbranch_vccz .LBB0_622
	v_mov_b32_e32 v152, v210
	v_mov_b32_e32 v153, v211
	v_mov_b32_e32 v154, v212
	v_mov_b32_e32 v155, v213
	v_and_b32_e32 v142, 0x1fcf, v146
	v_cvt_f32_u32_e32 v142, v142
	v_mul_f32_e32 v143, v152, v142
	v_mul_f32_e32 v144, v153, v142
	v_mul_f32_e32 v147, v154, v142
	v_mul_f32_e32 v154, v155, v142
	v_cvt_f64_f32_e32 v[142:143], v143
	v_cvt_f64_f32_e32 v[144:145], v144
	v_mul_f64 v[162:163], v[142:143], s[42:43]
	v_cvt_f64_f32_e32 v[152:153], v147
	v_mul_f64 v[164:165], v[144:145], s[42:43]
	v_rndne_f64_e32 v[162:163], v[162:163]
	v_mul_f64 v[166:167], v[152:153], s[42:43]
	v_rndne_f64_e32 v[164:165], v[164:165]
	v_fma_f64 v[142:143], v[142:143], s[42:43], -v[162:163]
	v_rndne_f64_e32 v[166:167], v[166:167]
	v_fma_f64 v[144:145], v[144:145], s[42:43], -v[164:165]
	v_mul_f64 v[142:143], v[142:143], s[44:45]
	v_fma_f64 v[152:153], v[152:153], s[42:43], -v[166:167]
	v_mul_f64 v[144:145], v[144:145], s[44:45]
	v_cvt_f32_f64_e32 v142, v[142:143]
	v_mul_f64 v[152:153], v[152:153], s[44:45]
	v_cvt_f32_f64_e32 v143, v[144:145]
	v_mul_f32_e32 v145, v142, v142
	v_cvt_i32_f64_e32 v147, v[162:163]
	v_cvt_i32_f64_e32 v161, v[164:165]
	v_cvt_f32_f64_e32 v144, v[152:153]
	v_mul_f32_e32 v152, v143, v143
	v_fmamk_f32 v163, v145, 0x3638ef1d, v159
	v_fmamk_f32 v164, v145, 0xb493f27e, v160
	v_cvt_i32_f64_e32 v162, v[166:167]
	v_mul_f32_e32 v153, v144, v144
	v_fmamk_f32 v165, v152, 0x3638ef1d, v159
	v_fmamk_f32 v166, v152, 0xb493f27e, v160
	v_fmaak_f32 v163, v145, v163, 0x3c088888
	v_fmaak_f32 v164, v145, v164, 0xbab60b61
	v_fmamk_f32 v167, v153, 0x3638ef1d, v159
	v_fmamk_f32 v170, v153, 0xb493f27e, v160
	v_fmaak_f32 v165, v152, v165, 0x3c088888
	v_fmaak_f32 v166, v152, v166, 0xbab60b61
	v_fmaak_f32 v163, v145, v163, 0xbe2aaaab
	v_fmaak_f32 v164, v145, v164, 0x3d2aaaab
	v_and_b32_e32 v147, 3, v147
	v_fmaak_f32 v167, v153, v167, 0x3c088888
	v_fmaak_f32 v170, v153, v170, 0xbab60b61
	v_fmaak_f32 v165, v152, v165, 0xbe2aaaab
	v_fmaak_f32 v166, v152, v166, 0x3d2aaaab
	v_fma_f32 v163, v145, v163, 1.0
	v_fma_f32 v164, v145, v164, -0.5
	v_and_b32_e32 v161, 3, v161
	v_fmaak_f32 v167, v153, v167, 0xbe2aaaab
	v_fmaak_f32 v170, v153, v170, 0x3d2aaaab
	v_fma_f32 v165, v152, v165, 1.0
	v_fma_f32 v166, v152, v166, -0.5
	v_mul_f32_e32 v142, v163, v142
	v_fma_f32 v145, v145, v164, 1.0
	v_cmp_eq_u32_e32 vcc, 2, v147
	v_and_b32_e32 v162, 3, v162
	v_fma_f32 v167, v153, v167, 1.0
	v_fma_f32 v170, v153, v170, -0.5
	v_mul_f32_e32 v143, v165, v143
	v_fma_f32 v152, v152, v166, 1.0
	v_cndmask_b32_e64 v163, v142, -v145, vcc
	v_cndmask_b32_e32 v164, v145, v142, vcc
	v_cmp_eq_u32_e32 vcc, 2, v161
	v_mul_f32_e32 v144, v167, v144
	v_fma_f32 v153, v153, v170, 1.0
	v_cndmask_b32_e64 v165, v143, -v152, vcc
	v_cndmask_b32_e32 v166, v152, v143, vcc
	v_cmp_eq_u32_e32 vcc, 2, v162
	v_cvt_f64_f32_e32 v[154:155], v154
	v_mul_f64 v[168:169], v[154:155], s[42:43]
	v_cndmask_b32_e64 v167, v144, -v153, vcc
	v_cndmask_b32_e32 v170, v153, v144, vcc
	v_cmp_eq_u32_e32 vcc, 1, v147
	v_rndne_f64_e32 v[168:169], v[168:169]
	v_fma_f64 v[154:155], v[154:155], s[42:43], -v[168:169]
	v_cndmask_b32_e64 v163, v163, -v142, vcc
	v_cndmask_b32_e64 v164, -v164, v145, vcc
	v_cmp_eq_u32_e32 vcc, 1, v161
	v_mul_f64 v[154:155], v[154:155], s[44:45]
	s_nop 0
	v_cndmask_b32_e64 v165, v165, -v143, vcc
	v_cndmask_b32_e64 v166, -v166, v152, vcc
	v_cmp_eq_u32_e32 vcc, 1, v162
	s_nop 1
	v_cndmask_b32_e64 v167, v167, -v144, vcc
	v_cndmask_b32_e64 v170, -v170, v153, vcc
	v_cmp_eq_u32_e32 vcc, 0, v147
	s_nop 1
	v_cndmask_b32_e32 v147, v163, v145, vcc
	v_cndmask_b32_e32 v163, v164, v142, vcc
	v_cmp_eq_u32_e32 vcc, 0, v161
	v_cvt_f32_f64_e32 v142, v[154:155]
	s_nop 0
	v_cndmask_b32_e32 v161, v165, v152, vcc
	v_cndmask_b32_e32 v164, v166, v143, vcc
	v_cmp_eq_u32_e32 vcc, 0, v162
	v_cvt_i32_f64_e32 v143, v[168:169]
	v_and_b32_e32 v143, 3, v143
	v_cndmask_b32_e32 v165, v170, v144, vcc
	v_mul_f32_e32 v144, v142, v142
	v_fmamk_f32 v145, v144, 0x3638ef1d, v159
	v_fmaak_f32 v145, v144, v145, 0x3c088888
	v_fmaak_f32 v145, v144, v145, 0xbe2aaaab
	v_fma_f32 v145, v144, v145, 1.0
	v_mul_f32_e32 v142, v145, v142
	v_fmamk_f32 v145, v144, 0xb493f27e, v160
	v_fmaak_f32 v145, v144, v145, 0xbab60b61
	v_fmaak_f32 v145, v144, v145, 0x3d2aaaab
	v_fma_f32 v145, v144, v145, -0.5
	v_cndmask_b32_e32 v162, v167, v153, vcc
	v_fma_f32 v144, v144, v145, 1.0
	v_cmp_eq_u32_e32 vcc, 2, v143
	v_cmp_eq_u32_e64 s[6:7], 1, v143
	s_nop 0
	v_cndmask_b32_e64 v145, v142, -v144, vcc
	v_cndmask_b32_e32 v152, v144, v142, vcc
	v_cndmask_b32_e64 v145, v145, -v142, s[6:7]
	v_cndmask_b32_e64 v152, -v152, v144, s[6:7]
	v_cmp_eq_u32_e32 vcc, 0, v143
	v_mul_f32_e32 v143, v126, v148
	s_mov_b64 s[6:7], 0
	v_cndmask_b32_e32 v154, v145, v144, vcc
	v_cndmask_b32_e32 v155, v152, v142, vcc
	v_mul_f32_e32 v144, v118, v148
	v_mul_f32_e32 v152, v143, v163
	v_mul_f32_e32 v145, v144, v163
	v_fmac_f32_e32 v152, v144, v147
	v_mul_f32_e32 v144, v119, v148
	v_fma_f32 v145, v143, v147, -v145
	v_mul_f32_e32 v143, v127, v148
	v_mul_f32_e32 v153, v144, v164
	v_fma_f32 v153, v143, v161, -v153
	v_mul_f32_e32 v166, v143, v164
	v_mul_f32_e32 v143, v128, v148
	v_fmac_f32_e32 v166, v144, v161
	v_mul_f32_e32 v144, v120, v148
	v_mul_f32_e32 v168, v143, v165
	v_mul_f32_e32 v167, v144, v165
	v_fmac_f32_e32 v168, v144, v162
	v_mul_f32_e32 v144, v121, v148
	v_or_b32_e32 v142, s78, v150
	v_fma_f32 v167, v143, v162, -v167
	v_mul_f32_e32 v143, v129, v148
	v_mul_f32_e32 v169, v144, v155
	v_fma_f32 v169, v143, v154, -v169
	v_mul_f32_e32 v170, v143, v155
	v_mad_u64_u32 v[142:143], s[0:1], v142, s77, v[140:141]
	v_fmac_f32_e32 v170, v144, v154
	v_mad_i32_i24 v143, v151, s77, v143
	v_cvt_pk_bf16_f32 v144, v145, v153
	v_cvt_pk_bf16_f32 v145, v167, v169
	v_cvt_pk_bf16_f32 v152, v152, v166
	v_cvt_pk_bf16_f32 v153, v168, v170
	v_mov_b32_e32 v222, v144
	v_mov_b32_e32 v223, v145
	v_mov_b32_e32 v224, v152
	v_mov_b32_e32 v225, v153
	s_nop 1
	v_permlane16_swap_b32_e32 v222, v224
	v_permlane16_swap_b32_e32 v223, v225
	v_lshl_add_u64 v[228:229], v[142:143], 0, v[226:227]
	global_store_dwordx4 v[228:229], v[222:225], off offset:128
	s_nop 0
	v_or_b32_e32 v144, s81, v150
	v_mov_b64_e32 v[142:143], s[24:25]
	v_mad_u64_u32 v[142:143], s[0:1], v144, s77, v[142:143]
	v_mul_f32_e32 v144, v122, v148
	v_mul_f32_e32 v145, v114, v148
	v_mul_f32_e32 v166, v145, v163
	v_mul_f32_e32 v163, v144, v163
	v_fma_f32 v166, v144, v147, -v166
	v_fmac_f32_e32 v163, v145, v147
	v_mul_f32_e32 v144, v123, v148
	v_mul_f32_e32 v145, v115, v148
	v_mul_f32_e32 v147, v145, v164
	v_mul_f32_e32 v164, v144, v164
	v_fma_f32 v147, v144, v161, -v147
	v_fmac_f32_e32 v164, v145, v161
	v_mul_f32_e32 v144, v124, v148
	v_mul_f32_e32 v145, v116, v148
	v_mul_f32_e32 v161, v145, v165
	v_mul_f32_e32 v165, v144, v165
	v_fma_f32 v161, v144, v162, -v161
	v_fmac_f32_e32 v165, v145, v162
	v_mul_f32_e32 v144, v125, v148
	v_mul_f32_e32 v145, v117, v148
	v_mad_i32_i24 v143, v151, s77, v143
	v_mul_f32_e32 v162, v145, v155
	v_mul_f32_e32 v155, v144, v155
	v_lshl_add_u64 v[152:153], v[142:143], 0, s[26:27]
	v_fmac_f32_e32 v155, v145, v154
	v_lshl_add_u64 v[142:143], v[142:143], 0, v[134:135]
	v_fma_f32 v162, v144, v154, -v162
	v_cvt_pk_bf16_f32 v144, v166, v147
	v_cvt_pk_bf16_f32 v145, v161, v162
	v_cvt_pk_bf16_f32 v154, v163, v164
	v_cvt_pk_bf16_f32 v155, v165, v155
	v_mov_b32_e32 v222, v144
	v_mov_b32_e32 v223, v145
	v_mov_b32_e32 v224, v154
	v_mov_b32_e32 v225, v155
	s_nop 1
	v_permlane16_swap_b32_e32 v222, v224
	v_permlane16_swap_b32_e32 v223, v225
	v_lshl_add_u64 v[228:229], v[142:143], 0, v[226:227]
	global_store_dwordx4 v[228:229], v[222:225], off offset:128
	s_nop 0
.LBB0_622:
	s_lshl_b32 s0, s8, 2
	s_ashr_i32 s1, s0, 31
	s_andn2_b64 vcc, exec, s[6:7]
	s_or_b64 s[54:55], s[0:1], s[12:13]
	s_cbranch_vccnz .LBB0_624
	v_lshl_add_u64 v[142:143], v[150:151], 0, s[54:55]
	v_mov_b64_e32 v[144:145], s[30:31]
	v_mad_u64_u32 v[144:145], s[0:1], v142, s77, v[144:145]
	v_mad_i32_i24 v145, v143, s77, v145
	v_lshl_add_u64 v[142:143], v[144:145], 0, v[134:135]
	v_pk_mul_f32 v[126:127], v[126:127], v[148:149] op_sel_hi:[1,0]
	v_pk_mul_f32 v[120:121], v[120:121], v[148:149] op_sel_hi:[1,0]
	v_pk_mul_f32 v[118:119], v[118:119], v[148:149] op_sel_hi:[1,0]
	v_pk_mul_f32 v[128:129], v[128:129], v[148:149] op_sel_hi:[1,0]
	v_cvt_pk_bf16_f32 v126, v126, v127
	v_lshl_add_u64 v[152:153], v[144:145], 0, s[40:41]
	v_cvt_pk_bf16_f32 v127, v128, v129
	v_mov_b32_e32 v222, v126
	v_mov_b32_e32 v223, v127
	v_cvt_pk_bf16_f32 v118, v118, v119
	v_cvt_pk_bf16_f32 v119, v120, v121
	v_pk_mul_f32 v[120:121], v[122:123], v[148:149] op_sel_hi:[1,0]
	v_mov_b32_e32 v224, v118
	v_mov_b32_e32 v225, v119
	s_nop 1
	v_permlane16_swap_b32_e32 v222, v224
	v_permlane16_swap_b32_e32 v223, v225
	v_lshl_add_u64 v[228:229], v[142:143], 0, v[226:227]
	global_store_dwordx4 v[228:229], v[222:225], off
	s_nop 0
	v_pk_mul_f32 v[118:119], v[124:125], v[148:149] op_sel_hi:[1,0]
	v_cvt_pk_bf16_f32 v120, v120, v121
	v_pk_mul_f32 v[116:117], v[116:117], v[148:149] op_sel_hi:[1,0]
	v_cvt_pk_bf16_f32 v121, v118, v119
	v_mov_b32_e32 v222, v120
	v_mov_b32_e32 v223, v121
	v_pk_mul_f32 v[114:115], v[114:115], v[148:149] op_sel_hi:[1,0]
	s_nop 0
	v_cvt_pk_bf16_f32 v154, v114, v115
	v_cvt_pk_bf16_f32 v155, v116, v117
	v_mov_b32_e32 v224, v154
	v_mov_b32_e32 v225, v155
	s_nop 1
	v_permlane16_swap_b32_e32 v222, v224
	v_permlane16_swap_b32_e32 v223, v225
	v_lshl_add_u64 v[228:229], v[142:143], 0, v[226:227]
	global_store_dwordx4 v[228:229], v[222:225], off offset:384
	s_nop 0
.LBB0_624:
	v_or_b32_e32 v122, 16, v146
	v_lshl_add_u64 v[114:115], v[152:153], 0, v[134:135]
	v_ashrrev_i32_e32 v123, 31, v122
	v_lshlrev_b64 v[114:115], 5, v[122:123]
	v_lshl_add_u64 v[114:115], s[10:11], 0, v[114:115]
	v_mov_b32_e32 v114, v182
	v_mov_b32_e32 v115, v183
	v_mov_b32_e32 v116, v184
	v_mov_b32_e32 v117, v185
	v_cndmask_b32_e64 v118, 0, 1, s[38:39]
	v_cmp_ne_u32_e64 s[6:7], 1, v118
	s_andn2_b64 vcc, exec, s[38:39]
	s_mov_b64 s[8:9], -1
	v_add_f32_e32 v114, v114, v115
	v_add_f32_e32 v115, v116, v117
	v_add_f32_e32 v114, v114, v115
	v_fmamk_f32 v114, v114, 0x3b800000, v158
	v_rsq_f32_e32 v114, v114
	v_lshlrev_b64 v[116:117], 3, v[122:123]
	v_mul_f32_e32 v114, 0x3e16c740, v114
	s_cbranch_vccnz .LBB0_626
	v_mov_b32_e32 v118, v210
	v_mov_b32_e32 v119, v211
	v_mov_b32_e32 v120, v212
	v_mov_b32_e32 v121, v213
	v_and_b32_e32 v115, 0x1fdf, v122
	v_cvt_f32_u32_e32 v115, v115
	v_mul_f32_e32 v118, v118, v115
	v_mul_f32_e32 v122, v119, v115
	v_cvt_f64_f32_e32 v[118:119], v118
	v_mul_f32_e32 v123, v120, v115
	v_mul_f32_e32 v115, v121, v115
	v_cvt_f64_f32_e32 v[120:121], v122
	v_mul_f64 v[126:127], v[118:119], s[42:43]
	v_cvt_f64_f32_e32 v[122:123], v123
	v_mul_f64 v[128:129], v[120:121], s[42:43]
	v_rndne_f64_e32 v[126:127], v[126:127]
	v_mul_f64 v[142:143], v[122:123], s[42:43]
	v_rndne_f64_e32 v[128:129], v[128:129]
	v_fma_f64 v[118:119], v[118:119], s[42:43], -v[126:127]
	v_rndne_f64_e32 v[142:143], v[142:143]
	v_fma_f64 v[120:121], v[120:121], s[42:43], -v[128:129]
	v_mul_f64 v[118:119], v[118:119], s[44:45]
	v_fma_f64 v[122:123], v[122:123], s[42:43], -v[142:143]
	v_mul_f64 v[120:121], v[120:121], s[44:45]
	v_cvt_f32_f64_e32 v118, v[118:119]
	v_mul_f64 v[122:123], v[122:123], s[44:45]
	v_cvt_f32_f64_e32 v119, v[120:121]
	v_mul_f32_e32 v121, v118, v118
	v_cvt_f64_f32_e32 v[124:125], v115
	v_cvt_i32_f64_e32 v115, v[126:127]
	v_cvt_i32_f64_e32 v126, v[128:129]
	v_cvt_f32_f64_e32 v120, v[122:123]
	v_mul_f32_e32 v122, v119, v119
	v_fmamk_f32 v128, v121, 0x3638ef1d, v159
	v_fmamk_f32 v129, v121, 0xb493f27e, v160
	v_cvt_i32_f64_e32 v127, v[142:143]
	v_mul_f32_e32 v123, v120, v120
	v_fmamk_f32 v142, v122, 0x3638ef1d, v159
	v_fmamk_f32 v143, v122, 0xb493f27e, v160
	v_fmaak_f32 v128, v121, v128, 0x3c088888
	v_fmaak_f32 v129, v121, v129, 0xbab60b61
	v_fmamk_f32 v147, v123, 0x3638ef1d, v159
	v_fmamk_f32 v148, v123, 0xb493f27e, v160
	v_fmaak_f32 v142, v122, v142, 0x3c088888
	v_fmaak_f32 v143, v122, v143, 0xbab60b61
	v_fmaak_f32 v128, v121, v128, 0xbe2aaaab
	v_fmaak_f32 v129, v121, v129, 0x3d2aaaab
	v_and_b32_e32 v115, 3, v115
	v_fmaak_f32 v147, v123, v147, 0x3c088888
	v_fmaak_f32 v148, v123, v148, 0xbab60b61
	v_fmaak_f32 v142, v122, v142, 0xbe2aaaab
	v_fmaak_f32 v143, v122, v143, 0x3d2aaaab
	v_fma_f32 v128, v121, v128, 1.0
	v_fma_f32 v129, v121, v129, -0.5
	v_and_b32_e32 v126, 3, v126
	v_fmaak_f32 v147, v123, v147, 0xbe2aaaab
	v_fmaak_f32 v148, v123, v148, 0x3d2aaaab
	v_fma_f32 v142, v122, v142, 1.0
	v_fma_f32 v143, v122, v143, -0.5
	v_mul_f32_e32 v118, v128, v118
	v_fma_f32 v121, v121, v129, 1.0
	v_cmp_eq_u32_e32 vcc, 2, v115
	v_and_b32_e32 v127, 3, v127
	v_fma_f32 v147, v123, v147, 1.0
	v_fma_f32 v148, v123, v148, -0.5
	v_mul_f32_e32 v119, v142, v119
	v_fma_f32 v122, v122, v143, 1.0
	v_cndmask_b32_e64 v128, v118, -v121, vcc
	v_cndmask_b32_e32 v129, v121, v118, vcc
	v_cmp_eq_u32_e32 vcc, 2, v126
	v_mul_f32_e32 v120, v147, v120
	v_fma_f32 v123, v123, v148, 1.0
	v_cndmask_b32_e64 v142, v119, -v122, vcc
	v_cndmask_b32_e32 v143, v122, v119, vcc
	v_cmp_eq_u32_e32 vcc, 2, v127
	v_mul_f64 v[144:145], v[124:125], s[42:43]
	v_rndne_f64_e32 v[144:145], v[144:145]
	v_cndmask_b32_e64 v147, v120, -v123, vcc
	v_cndmask_b32_e32 v148, v123, v120, vcc
	v_cmp_eq_u32_e32 vcc, 1, v115
	v_fma_f64 v[124:125], v[124:125], s[42:43], -v[144:145]
	v_mul_f64 v[124:125], v[124:125], s[44:45]
	v_cndmask_b32_e64 v128, v128, -v118, vcc
	v_cndmask_b32_e64 v129, -v129, v121, vcc
	v_cmp_eq_u32_e32 vcc, 1, v126
	s_nop 1
	v_cndmask_b32_e64 v142, v142, -v119, vcc
	v_cndmask_b32_e64 v143, -v143, v122, vcc
	v_cmp_eq_u32_e32 vcc, 1, v127
	s_nop 1
	v_cndmask_b32_e64 v147, v147, -v120, vcc
	v_cndmask_b32_e64 v148, -v148, v123, vcc
	v_cmp_eq_u32_e32 vcc, 0, v115
	s_nop 1
	v_cndmask_b32_e32 v115, v128, v121, vcc
	v_cndmask_b32_e32 v128, v129, v118, vcc
	v_cmp_eq_u32_e32 vcc, 0, v126
	v_cvt_f32_f64_e32 v118, v[124:125]
	s_nop 0
	v_cndmask_b32_e32 v126, v142, v122, vcc
	v_cndmask_b32_e32 v129, v143, v119, vcc
	v_cmp_eq_u32_e32 vcc, 0, v127
	v_cvt_i32_f64_e32 v119, v[144:145]
	v_and_b32_e32 v119, 3, v119
	v_cndmask_b32_e32 v142, v148, v120, vcc
	v_mul_f32_e32 v120, v118, v118
	v_fmamk_f32 v121, v120, 0x3638ef1d, v159
	v_fmaak_f32 v121, v120, v121, 0x3c088888
	v_fmaak_f32 v121, v120, v121, 0xbe2aaaab
	v_fma_f32 v121, v120, v121, 1.0
	v_mul_f32_e32 v118, v121, v118
	v_fmamk_f32 v121, v120, 0xb493f27e, v160
	v_fmaak_f32 v121, v120, v121, 0xbab60b61
	v_fmaak_f32 v121, v120, v121, 0x3d2aaaab
	v_fma_f32 v121, v120, v121, -0.5
	v_cndmask_b32_e32 v127, v147, v123, vcc
	v_fma_f32 v120, v120, v121, 1.0
	v_cmp_eq_u32_e32 vcc, 2, v119
	v_cmp_eq_u32_e64 s[8:9], 1, v119
	s_nop 0
	v_cndmask_b32_e64 v121, v118, -v120, vcc
	v_cndmask_b32_e32 v122, v120, v118, vcc
	v_cndmask_b32_e64 v121, v121, -v118, s[8:9]
	v_cndmask_b32_e64 v122, -v122, v120, s[8:9]
	v_cmp_eq_u32_e32 vcc, 0, v119
	v_mul_f32_e32 v119, v110, v114
	s_mov_b64 s[8:9], 0
	v_cndmask_b32_e32 v124, v121, v120, vcc
	v_cndmask_b32_e32 v125, v122, v118, vcc
	v_mul_f32_e32 v120, v102, v114
	v_mul_f32_e32 v122, v119, v128
	v_mul_f32_e32 v121, v120, v128
	v_fmac_f32_e32 v122, v120, v115
	v_mul_f32_e32 v120, v103, v114
	v_fma_f32 v121, v119, v115, -v121
	v_mul_f32_e32 v119, v111, v114
	v_mul_f32_e32 v123, v120, v129
	v_fma_f32 v123, v119, v126, -v123
	v_mul_f32_e32 v143, v119, v129
	v_mul_f32_e32 v119, v112, v114
	v_fmac_f32_e32 v143, v120, v126
	v_mul_f32_e32 v120, v104, v114
	v_mul_f32_e32 v145, v119, v142
	v_mul_f32_e32 v144, v120, v142
	v_fmac_f32_e32 v145, v120, v127
	v_mul_f32_e32 v120, v105, v114
	v_or_b32_e32 v118, s78, v116
	v_fma_f32 v144, v119, v127, -v144
	v_mul_f32_e32 v119, v113, v114
	v_mul_f32_e32 v147, v120, v125
	v_fma_f32 v147, v119, v124, -v147
	v_mul_f32_e32 v148, v119, v125
	v_mad_u64_u32 v[118:119], s[0:1], v118, s77, v[140:141]
	v_fmac_f32_e32 v148, v120, v124
	v_mad_i32_i24 v119, v117, s77, v119
	v_cvt_pk_bf16_f32 v120, v121, v123
	v_cvt_pk_bf16_f32 v121, v144, v147
	v_cvt_pk_bf16_f32 v122, v122, v143
	v_cvt_pk_bf16_f32 v123, v145, v148
	v_mov_b32_e32 v222, v120
	v_mov_b32_e32 v223, v121
	v_mov_b32_e32 v224, v122
	v_mov_b32_e32 v225, v123
	s_nop 1
	v_permlane16_swap_b32_e32 v222, v224
	v_permlane16_swap_b32_e32 v223, v225
	v_lshl_add_u64 v[228:229], v[118:119], 0, v[226:227]
	global_store_dwordx4 v[228:229], v[222:225], off offset:128
	s_nop 0
	v_mul_f32_e32 v123, v98, v114
	v_mul_f32_e32 v122, v106, v114
	v_mul_f32_e32 v143, v123, v128
	v_fma_f32 v143, v122, v115, -v143
	v_mul_f32_e32 v128, v122, v128
	v_mul_f32_e32 v122, v99, v114
	v_fmac_f32_e32 v128, v123, v115
	v_mul_f32_e32 v115, v107, v114
	v_mul_f32_e32 v123, v122, v129
	v_fma_f32 v144, v115, v126, -v123
	v_mul_f32_e32 v115, v115, v129
	v_fmac_f32_e32 v115, v122, v126
	v_mul_f32_e32 v122, v108, v114
	v_mul_f32_e32 v123, v100, v114
	v_or_b32_e32 v120, s81, v116
	v_mov_b64_e32 v[118:119], s[24:25]
	v_mul_f32_e32 v126, v123, v142
	v_mul_f32_e32 v129, v122, v142
	v_mad_u64_u32 v[120:121], s[0:1], v120, s77, v[118:119]
	v_fma_f32 v126, v122, v127, -v126
	v_fmac_f32_e32 v129, v123, v127
	v_mul_f32_e32 v122, v109, v114
	v_mul_f32_e32 v123, v101, v114
	v_mad_i32_i24 v121, v117, s77, v121
	v_mul_f32_e32 v127, v123, v125
	v_mul_f32_e32 v142, v122, v125
	v_lshl_add_u64 v[118:119], v[120:121], 0, s[26:27]
	v_fma_f32 v127, v122, v124, -v127
	v_fmac_f32_e32 v142, v123, v124
	v_lshl_add_u64 v[122:123], v[120:121], 0, v[134:135]
	v_cvt_pk_bf16_f32 v124, v143, v144
	v_cvt_pk_bf16_f32 v125, v126, v127
	v_cvt_pk_bf16_f32 v120, v128, v115
	v_cvt_pk_bf16_f32 v121, v129, v142
	v_mov_b32_e32 v222, v124
	v_mov_b32_e32 v223, v125
	v_mov_b32_e32 v224, v120
	v_mov_b32_e32 v225, v121
	s_nop 1
	v_permlane16_swap_b32_e32 v222, v224
	v_permlane16_swap_b32_e32 v223, v225
	v_lshl_add_u64 v[228:229], v[122:123], 0, v[226:227]
	global_store_dwordx4 v[228:229], v[222:225], off offset:128
	s_nop 0
.LBB0_626:
	s_andn2_b64 vcc, exec, s[8:9]
	s_cbranch_vccnz .LBB0_628
	v_lshl_add_u64 v[116:117], v[116:117], 0, s[54:55]
	v_mov_b64_e32 v[118:119], s[30:31]
	v_mad_u64_u32 v[118:119], s[0:1], v116, s77, v[118:119]
	v_mad_i32_i24 v119, v117, s77, v119
	v_lshl_add_u64 v[116:117], v[118:119], 0, v[134:135]
	v_pk_mul_f32 v[110:111], v[110:111], v[114:115] op_sel_hi:[1,0]
	v_pk_mul_f32 v[104:105], v[104:105], v[114:115] op_sel_hi:[1,0]
	v_pk_mul_f32 v[102:103], v[102:103], v[114:115] op_sel_hi:[1,0]
	v_pk_mul_f32 v[112:113], v[112:113], v[114:115] op_sel_hi:[1,0]
	v_cvt_pk_bf16_f32 v110, v110, v111
	v_lshl_add_u64 v[118:119], v[118:119], 0, s[40:41]
	v_cvt_pk_bf16_f32 v111, v112, v113
	v_mov_b32_e32 v222, v110
	v_mov_b32_e32 v223, v111
	v_cvt_pk_bf16_f32 v102, v102, v103
	v_cvt_pk_bf16_f32 v103, v104, v105
	v_pk_mul_f32 v[104:105], v[106:107], v[114:115] op_sel_hi:[1,0]
	v_mov_b32_e32 v224, v102
	v_mov_b32_e32 v225, v103
	s_nop 1
	v_permlane16_swap_b32_e32 v222, v224
	v_permlane16_swap_b32_e32 v223, v225
	v_lshl_add_u64 v[228:229], v[116:117], 0, v[226:227]
	global_store_dwordx4 v[228:229], v[222:225], off
	s_nop 0
	v_pk_mul_f32 v[102:103], v[108:109], v[114:115] op_sel_hi:[1,0]
	v_cvt_pk_bf16_f32 v104, v104, v105
	v_pk_mul_f32 v[100:101], v[100:101], v[114:115] op_sel_hi:[1,0]
	v_cvt_pk_bf16_f32 v105, v102, v103
	v_mov_b32_e32 v222, v104
	v_mov_b32_e32 v223, v105
	v_pk_mul_f32 v[98:99], v[98:99], v[114:115] op_sel_hi:[1,0]
	s_nop 0
	v_cvt_pk_bf16_f32 v120, v98, v99
	v_cvt_pk_bf16_f32 v121, v100, v101
	v_mov_b32_e32 v224, v120
	v_mov_b32_e32 v225, v121
	s_nop 1
	v_permlane16_swap_b32_e32 v222, v224
	v_permlane16_swap_b32_e32 v223, v225
	v_lshl_add_u64 v[228:229], v[116:117], 0, v[226:227]
	global_store_dwordx4 v[228:229], v[222:225], off offset:384
	s_nop 0
.LBB0_628:
	v_or_b32_e32 v106, 32, v146
	v_lshl_add_u64 v[98:99], v[118:119], 0, v[134:135]
	v_ashrrev_i32_e32 v107, 31, v106
	v_lshlrev_b64 v[98:99], 5, v[106:107]
	v_lshl_add_u64 v[98:99], s[10:11], 0, v[98:99]
	v_mov_b32_e32 v98, v186
	v_mov_b32_e32 v99, v187
	v_mov_b32_e32 v100, v188
	v_mov_b32_e32 v101, v189
	s_and_b64 vcc, exec, s[6:7]
	s_mov_b64 s[8:9], -1
	v_add_f32_e32 v98, v98, v99
	v_add_f32_e32 v99, v100, v101
	v_add_f32_e32 v98, v98, v99
	v_fmamk_f32 v98, v98, 0x3b800000, v158
	v_rsq_f32_e32 v98, v98
	v_lshlrev_b64 v[100:101], 3, v[106:107]
	v_mul_f32_e32 v98, 0x3e16c740, v98
	s_cbranch_vccnz .LBB0_630
	v_mov_b32_e32 v102, v210
	v_mov_b32_e32 v103, v211
	v_mov_b32_e32 v104, v212
	v_mov_b32_e32 v105, v213
	v_and_b32_e32 v99, 0x1fef, v106
	v_cvt_f32_u32_e32 v99, v99
	v_mul_f32_e32 v102, v102, v99
	v_mul_f32_e32 v106, v103, v99
	v_cvt_f64_f32_e32 v[102:103], v102
	v_mul_f32_e32 v107, v104, v99
	v_mul_f32_e32 v99, v105, v99
	v_cvt_f64_f32_e32 v[104:105], v106
	v_mul_f64 v[110:111], v[102:103], s[42:43]
	v_cvt_f64_f32_e32 v[106:107], v107
	v_mul_f64 v[112:113], v[104:105], s[42:43]
	v_rndne_f64_e32 v[110:111], v[110:111]
	v_mul_f64 v[114:115], v[106:107], s[42:43]
	v_rndne_f64_e32 v[112:113], v[112:113]
	v_fma_f64 v[102:103], v[102:103], s[42:43], -v[110:111]
	v_rndne_f64_e32 v[114:115], v[114:115]
	v_fma_f64 v[104:105], v[104:105], s[42:43], -v[112:113]
	v_mul_f64 v[102:103], v[102:103], s[44:45]
	v_fma_f64 v[106:107], v[106:107], s[42:43], -v[114:115]
	v_mul_f64 v[104:105], v[104:105], s[44:45]
	v_cvt_f32_f64_e32 v102, v[102:103]
	v_mul_f64 v[106:107], v[106:107], s[44:45]
	v_cvt_f32_f64_e32 v103, v[104:105]
	v_mul_f32_e32 v105, v102, v102
	v_cvt_f64_f32_e32 v[108:109], v99
	v_cvt_i32_f64_e32 v99, v[110:111]
	v_cvt_i32_f64_e32 v110, v[112:113]
	v_cvt_f32_f64_e32 v104, v[106:107]
	v_mul_f32_e32 v106, v103, v103
	v_fmamk_f32 v112, v105, 0x3638ef1d, v159
	v_fmamk_f32 v113, v105, 0xb493f27e, v160
	v_cvt_i32_f64_e32 v111, v[114:115]
	v_mul_f32_e32 v107, v104, v104
	v_fmamk_f32 v114, v106, 0x3638ef1d, v159
	v_fmamk_f32 v115, v106, 0xb493f27e, v160
	v_fmaak_f32 v112, v105, v112, 0x3c088888
	v_fmaak_f32 v113, v105, v113, 0xbab60b61
	v_fmamk_f32 v118, v107, 0x3638ef1d, v159
	v_fmamk_f32 v119, v107, 0xb493f27e, v160
	v_fmaak_f32 v114, v106, v114, 0x3c088888
	v_fmaak_f32 v115, v106, v115, 0xbab60b61
	v_fmaak_f32 v112, v105, v112, 0xbe2aaaab
	v_fmaak_f32 v113, v105, v113, 0x3d2aaaab
	v_and_b32_e32 v99, 3, v99
	v_fmaak_f32 v118, v107, v118, 0x3c088888
	v_fmaak_f32 v119, v107, v119, 0xbab60b61
	v_fmaak_f32 v114, v106, v114, 0xbe2aaaab
	v_fmaak_f32 v115, v106, v115, 0x3d2aaaab
	v_fma_f32 v112, v105, v112, 1.0
	v_fma_f32 v113, v105, v113, -0.5
	v_and_b32_e32 v110, 3, v110
	v_fmaak_f32 v118, v107, v118, 0xbe2aaaab
	v_fmaak_f32 v119, v107, v119, 0x3d2aaaab
	v_fma_f32 v114, v106, v114, 1.0
	v_fma_f32 v115, v106, v115, -0.5
	v_mul_f32_e32 v102, v112, v102
	v_fma_f32 v105, v105, v113, 1.0
	v_cmp_eq_u32_e32 vcc, 2, v99
	v_and_b32_e32 v111, 3, v111
	v_fma_f32 v118, v107, v118, 1.0
	v_fma_f32 v119, v107, v119, -0.5
	v_mul_f32_e32 v103, v114, v103
	v_fma_f32 v106, v106, v115, 1.0
	v_cndmask_b32_e64 v112, v102, -v105, vcc
	v_cndmask_b32_e32 v113, v105, v102, vcc
	v_cmp_eq_u32_e32 vcc, 2, v110
	v_mul_f32_e32 v104, v118, v104
	v_fma_f32 v107, v107, v119, 1.0
	v_cndmask_b32_e64 v114, v103, -v106, vcc
	v_cndmask_b32_e32 v115, v106, v103, vcc
	v_cmp_eq_u32_e32 vcc, 2, v111
	v_mul_f64 v[116:117], v[108:109], s[42:43]
	v_rndne_f64_e32 v[116:117], v[116:117]
	v_cndmask_b32_e64 v118, v104, -v107, vcc
	v_cndmask_b32_e32 v119, v107, v104, vcc
	v_cmp_eq_u32_e32 vcc, 1, v99
	v_fma_f64 v[108:109], v[108:109], s[42:43], -v[116:117]
	v_mul_f64 v[108:109], v[108:109], s[44:45]
	v_cndmask_b32_e64 v112, v112, -v102, vcc
	v_cndmask_b32_e64 v113, -v113, v105, vcc
	v_cmp_eq_u32_e32 vcc, 1, v110
	s_nop 1
	v_cndmask_b32_e64 v114, v114, -v103, vcc
	v_cndmask_b32_e64 v115, -v115, v106, vcc
	v_cmp_eq_u32_e32 vcc, 1, v111
	s_nop 1
	v_cndmask_b32_e64 v118, v118, -v104, vcc
	v_cndmask_b32_e64 v119, -v119, v107, vcc
	v_cmp_eq_u32_e32 vcc, 0, v99
	s_nop 1
	v_cndmask_b32_e32 v99, v112, v105, vcc
	v_cndmask_b32_e32 v112, v113, v102, vcc
	v_cmp_eq_u32_e32 vcc, 0, v110
	v_cvt_f32_f64_e32 v102, v[108:109]
	s_nop 0
	v_cndmask_b32_e32 v110, v114, v106, vcc
	v_cndmask_b32_e32 v113, v115, v103, vcc
	v_cmp_eq_u32_e32 vcc, 0, v111
	v_cvt_i32_f64_e32 v103, v[116:117]
	v_and_b32_e32 v103, 3, v103
	v_cndmask_b32_e32 v114, v119, v104, vcc
	v_mul_f32_e32 v104, v102, v102
	v_fmamk_f32 v105, v104, 0x3638ef1d, v159
	v_fmaak_f32 v105, v104, v105, 0x3c088888
	v_fmaak_f32 v105, v104, v105, 0xbe2aaaab
	v_fma_f32 v105, v104, v105, 1.0
	v_mul_f32_e32 v102, v105, v102
	v_fmamk_f32 v105, v104, 0xb493f27e, v160
	v_fmaak_f32 v105, v104, v105, 0xbab60b61
	v_fmaak_f32 v105, v104, v105, 0x3d2aaaab
	v_fma_f32 v105, v104, v105, -0.5
	v_cndmask_b32_e32 v111, v118, v107, vcc
	v_fma_f32 v104, v104, v105, 1.0
	v_cmp_eq_u32_e32 vcc, 2, v103
	v_cmp_eq_u32_e64 s[8:9], 1, v103
	s_nop 0
	v_cndmask_b32_e64 v105, v102, -v104, vcc
	v_cndmask_b32_e32 v106, v104, v102, vcc
	v_cndmask_b32_e64 v105, v105, -v102, s[8:9]
	v_cndmask_b32_e64 v106, -v106, v104, s[8:9]
	v_cmp_eq_u32_e32 vcc, 0, v103
	v_mul_f32_e32 v103, v94, v98
	s_mov_b64 s[8:9], 0
	v_cndmask_b32_e32 v108, v105, v104, vcc
	v_cndmask_b32_e32 v109, v106, v102, vcc
	v_mul_f32_e32 v104, v86, v98
	v_mul_f32_e32 v106, v103, v112
	v_mul_f32_e32 v105, v104, v112
	v_fmac_f32_e32 v106, v104, v99
	v_mul_f32_e32 v104, v87, v98
	v_fma_f32 v105, v103, v99, -v105
	v_mul_f32_e32 v103, v95, v98
	v_mul_f32_e32 v107, v104, v113
	v_fma_f32 v107, v103, v110, -v107
	v_mul_f32_e32 v115, v103, v113
	v_mul_f32_e32 v103, v96, v98
	v_fmac_f32_e32 v115, v104, v110
	v_mul_f32_e32 v104, v88, v98
	v_mul_f32_e32 v117, v103, v114
	v_mul_f32_e32 v116, v104, v114
	v_fmac_f32_e32 v117, v104, v111
	v_mul_f32_e32 v104, v89, v98
	v_or_b32_e32 v102, s78, v100
	v_fma_f32 v116, v103, v111, -v116
	v_mul_f32_e32 v103, v97, v98
	v_mul_f32_e32 v118, v104, v109
	v_fma_f32 v118, v103, v108, -v118
	v_mul_f32_e32 v119, v103, v109
	v_mad_u64_u32 v[102:103], s[0:1], v102, s77, v[140:141]
	v_fmac_f32_e32 v119, v104, v108
	v_mad_i32_i24 v103, v101, s77, v103
	v_cvt_pk_bf16_f32 v104, v105, v107
	v_cvt_pk_bf16_f32 v105, v116, v118
	v_cvt_pk_bf16_f32 v106, v106, v115
	v_cvt_pk_bf16_f32 v107, v117, v119
	v_mov_b32_e32 v222, v104
	v_mov_b32_e32 v223, v105
	v_mov_b32_e32 v224, v106
	v_mov_b32_e32 v225, v107
	s_nop 1
	v_permlane16_swap_b32_e32 v222, v224
	v_permlane16_swap_b32_e32 v223, v225
	v_lshl_add_u64 v[228:229], v[102:103], 0, v[226:227]
	global_store_dwordx4 v[228:229], v[222:225], off offset:128
	s_nop 0
	v_mul_f32_e32 v107, v82, v98
	v_mul_f32_e32 v106, v90, v98
	v_mul_f32_e32 v115, v107, v112
	v_fma_f32 v115, v106, v99, -v115
	v_mul_f32_e32 v112, v106, v112
	v_mul_f32_e32 v106, v83, v98
	v_fmac_f32_e32 v112, v107, v99
	v_mul_f32_e32 v99, v91, v98
	v_mul_f32_e32 v107, v106, v113
	v_fma_f32 v116, v99, v110, -v107
	v_mul_f32_e32 v99, v99, v113
	v_fmac_f32_e32 v99, v106, v110
	v_mul_f32_e32 v106, v92, v98
	v_mul_f32_e32 v107, v84, v98
	v_or_b32_e32 v104, s81, v100
	v_mov_b64_e32 v[102:103], s[24:25]
	v_mul_f32_e32 v110, v107, v114
	v_mul_f32_e32 v113, v106, v114
	v_mad_u64_u32 v[104:105], s[0:1], v104, s77, v[102:103]
	v_fma_f32 v110, v106, v111, -v110
	v_fmac_f32_e32 v113, v107, v111
	v_mul_f32_e32 v106, v93, v98
	v_mul_f32_e32 v107, v85, v98
	v_mad_i32_i24 v105, v101, s77, v105
	v_mul_f32_e32 v111, v107, v109
	v_mul_f32_e32 v114, v106, v109
	v_lshl_add_u64 v[102:103], v[104:105], 0, s[26:27]
	v_fma_f32 v111, v106, v108, -v111
	v_fmac_f32_e32 v114, v107, v108
	v_lshl_add_u64 v[106:107], v[104:105], 0, v[134:135]
	v_cvt_pk_bf16_f32 v108, v115, v116
	v_cvt_pk_bf16_f32 v109, v110, v111
	v_cvt_pk_bf16_f32 v104, v112, v99
	v_cvt_pk_bf16_f32 v105, v113, v114
	v_mov_b32_e32 v222, v108
	v_mov_b32_e32 v223, v109
	v_mov_b32_e32 v224, v104
	v_mov_b32_e32 v225, v105
	s_nop 1
	v_permlane16_swap_b32_e32 v222, v224
	v_permlane16_swap_b32_e32 v223, v225
	v_lshl_add_u64 v[228:229], v[106:107], 0, v[226:227]
	global_store_dwordx4 v[228:229], v[222:225], off offset:128
	s_nop 0
.LBB0_630:
	s_andn2_b64 vcc, exec, s[8:9]
	s_cbranch_vccnz .LBB0_632
	v_lshl_add_u64 v[100:101], v[100:101], 0, s[54:55]
	v_mov_b64_e32 v[102:103], s[30:31]
	v_mad_u64_u32 v[102:103], s[0:1], v100, s77, v[102:103]
	v_mad_i32_i24 v103, v101, s77, v103
	v_lshl_add_u64 v[100:101], v[102:103], 0, v[134:135]
	v_pk_mul_f32 v[94:95], v[94:95], v[98:99] op_sel_hi:[1,0]
	v_pk_mul_f32 v[88:89], v[88:89], v[98:99] op_sel_hi:[1,0]
	v_pk_mul_f32 v[86:87], v[86:87], v[98:99] op_sel_hi:[1,0]
	v_pk_mul_f32 v[96:97], v[96:97], v[98:99] op_sel_hi:[1,0]
	v_cvt_pk_bf16_f32 v94, v94, v95
	v_lshl_add_u64 v[102:103], v[102:103], 0, s[40:41]
	v_cvt_pk_bf16_f32 v95, v96, v97
	v_mov_b32_e32 v222, v94
	v_mov_b32_e32 v223, v95
	v_cvt_pk_bf16_f32 v86, v86, v87
	v_cvt_pk_bf16_f32 v87, v88, v89
	v_pk_mul_f32 v[88:89], v[90:91], v[98:99] op_sel_hi:[1,0]
	v_mov_b32_e32 v224, v86
	v_mov_b32_e32 v225, v87
	s_nop 1
	v_permlane16_swap_b32_e32 v222, v224
	v_permlane16_swap_b32_e32 v223, v225
	v_lshl_add_u64 v[228:229], v[100:101], 0, v[226:227]
	global_store_dwordx4 v[228:229], v[222:225], off
	s_nop 0
	v_pk_mul_f32 v[86:87], v[92:93], v[98:99] op_sel_hi:[1,0]
	v_cvt_pk_bf16_f32 v88, v88, v89
	v_pk_mul_f32 v[84:85], v[84:85], v[98:99] op_sel_hi:[1,0]
	v_cvt_pk_bf16_f32 v89, v86, v87
	v_mov_b32_e32 v222, v88
	v_mov_b32_e32 v223, v89
	v_pk_mul_f32 v[82:83], v[82:83], v[98:99] op_sel_hi:[1,0]
	s_nop 0
	v_cvt_pk_bf16_f32 v104, v82, v83
	v_cvt_pk_bf16_f32 v105, v84, v85
	v_mov_b32_e32 v224, v104
	v_mov_b32_e32 v225, v105
	s_nop 1
	v_permlane16_swap_b32_e32 v222, v224
	v_permlane16_swap_b32_e32 v223, v225
	v_lshl_add_u64 v[228:229], v[100:101], 0, v[226:227]
	global_store_dwordx4 v[228:229], v[222:225], off offset:384
	s_nop 0
.LBB0_632:
	v_or_b32_e32 v90, 48, v146
	v_lshl_add_u64 v[82:83], v[102:103], 0, v[134:135]
	v_ashrrev_i32_e32 v91, 31, v90
	v_lshlrev_b64 v[82:83], 5, v[90:91]
	v_lshl_add_u64 v[82:83], s[10:11], 0, v[82:83]
	v_mov_b32_e32 v82, v190
	v_mov_b32_e32 v83, v191
	v_mov_b32_e32 v84, v192
	v_mov_b32_e32 v85, v193
	s_and_b64 vcc, exec, s[6:7]
	s_mov_b64 s[8:9], -1
	v_add_f32_e32 v82, v82, v83
	v_add_f32_e32 v83, v84, v85
	v_add_f32_e32 v82, v82, v83
	v_fmamk_f32 v82, v82, 0x3b800000, v158
	v_rsq_f32_e32 v82, v82
	v_lshlrev_b64 v[84:85], 3, v[90:91]
	v_mul_f32_e32 v82, 0x3e16c740, v82
	s_cbranch_vccnz .LBB0_634
	v_mov_b32_e32 v86, v210
	v_mov_b32_e32 v87, v211
	v_mov_b32_e32 v88, v212
	v_mov_b32_e32 v89, v213
	v_and_b32_e32 v83, 0x1fff, v90
	v_cvt_f32_u32_e32 v83, v83
	v_mul_f32_e32 v86, v86, v83
	v_mul_f32_e32 v90, v87, v83
	v_cvt_f64_f32_e32 v[86:87], v86
	v_mul_f32_e32 v91, v88, v83
	v_mul_f32_e32 v83, v89, v83
	v_cvt_f64_f32_e32 v[88:89], v90
	v_mul_f64 v[94:95], v[86:87], s[42:43]
	v_cvt_f64_f32_e32 v[90:91], v91
	v_mul_f64 v[96:97], v[88:89], s[42:43]
	v_rndne_f64_e32 v[94:95], v[94:95]
	v_mul_f64 v[98:99], v[90:91], s[42:43]
	v_rndne_f64_e32 v[96:97], v[96:97]
	v_fma_f64 v[86:87], v[86:87], s[42:43], -v[94:95]
	v_rndne_f64_e32 v[98:99], v[98:99]
	v_fma_f64 v[88:89], v[88:89], s[42:43], -v[96:97]
	v_mul_f64 v[86:87], v[86:87], s[44:45]
	v_fma_f64 v[90:91], v[90:91], s[42:43], -v[98:99]
	v_mul_f64 v[88:89], v[88:89], s[44:45]
	v_cvt_f32_f64_e32 v86, v[86:87]
	v_mul_f64 v[90:91], v[90:91], s[44:45]
	v_cvt_f32_f64_e32 v87, v[88:89]
	v_mul_f32_e32 v89, v86, v86
	v_cvt_f64_f32_e32 v[92:93], v83
	v_cvt_i32_f64_e32 v83, v[94:95]
	v_cvt_i32_f64_e32 v94, v[96:97]
	v_cvt_f32_f64_e32 v88, v[90:91]
	v_mul_f32_e32 v90, v87, v87
	v_fmamk_f32 v96, v89, 0x3638ef1d, v159
	v_fmamk_f32 v97, v89, 0xb493f27e, v160
	v_cvt_i32_f64_e32 v95, v[98:99]
	v_mul_f32_e32 v91, v88, v88
	v_fmamk_f32 v98, v90, 0x3638ef1d, v159
	v_fmamk_f32 v99, v90, 0xb493f27e, v160
	v_fmaak_f32 v96, v89, v96, 0x3c088888
	v_fmaak_f32 v97, v89, v97, 0xbab60b61
	v_fmamk_f32 v102, v91, 0x3638ef1d, v159
	v_fmamk_f32 v103, v91, 0xb493f27e, v160
	v_fmaak_f32 v98, v90, v98, 0x3c088888
	v_fmaak_f32 v99, v90, v99, 0xbab60b61
	v_fmaak_f32 v96, v89, v96, 0xbe2aaaab
	v_fmaak_f32 v97, v89, v97, 0x3d2aaaab
	v_and_b32_e32 v83, 3, v83
	v_fmaak_f32 v102, v91, v102, 0x3c088888
	v_fmaak_f32 v103, v91, v103, 0xbab60b61
	v_fmaak_f32 v98, v90, v98, 0xbe2aaaab
	v_fmaak_f32 v99, v90, v99, 0x3d2aaaab
	v_fma_f32 v96, v89, v96, 1.0
	v_fma_f32 v97, v89, v97, -0.5
	v_and_b32_e32 v94, 3, v94
	v_fmaak_f32 v102, v91, v102, 0xbe2aaaab
	v_fmaak_f32 v103, v91, v103, 0x3d2aaaab
	v_fma_f32 v98, v90, v98, 1.0
	v_fma_f32 v99, v90, v99, -0.5
	v_mul_f32_e32 v86, v96, v86
	v_fma_f32 v89, v89, v97, 1.0
	v_cmp_eq_u32_e32 vcc, 2, v83
	v_and_b32_e32 v95, 3, v95
	v_fma_f32 v102, v91, v102, 1.0
	v_fma_f32 v103, v91, v103, -0.5
	v_mul_f32_e32 v87, v98, v87
	v_fma_f32 v90, v90, v99, 1.0
	v_cndmask_b32_e64 v96, v86, -v89, vcc
	v_cndmask_b32_e32 v97, v89, v86, vcc
	v_cmp_eq_u32_e32 vcc, 2, v94
	v_mul_f32_e32 v88, v102, v88
	v_fma_f32 v91, v91, v103, 1.0
	v_cndmask_b32_e64 v98, v87, -v90, vcc
	v_cndmask_b32_e32 v99, v90, v87, vcc
	v_cmp_eq_u32_e32 vcc, 2, v95
	v_mul_f64 v[100:101], v[92:93], s[42:43]
	v_rndne_f64_e32 v[100:101], v[100:101]
	v_cndmask_b32_e64 v102, v88, -v91, vcc
	v_cndmask_b32_e32 v103, v91, v88, vcc
	v_cmp_eq_u32_e32 vcc, 1, v83
	v_fma_f64 v[92:93], v[92:93], s[42:43], -v[100:101]
	v_mul_f64 v[92:93], v[92:93], s[44:45]
	v_cndmask_b32_e64 v96, v96, -v86, vcc
	v_cndmask_b32_e64 v97, -v97, v89, vcc
	v_cmp_eq_u32_e32 vcc, 1, v94
	s_nop 1
	v_cndmask_b32_e64 v98, v98, -v87, vcc
	v_cndmask_b32_e64 v99, -v99, v90, vcc
	v_cmp_eq_u32_e32 vcc, 1, v95
	s_nop 1
	v_cndmask_b32_e64 v102, v102, -v88, vcc
	v_cndmask_b32_e64 v103, -v103, v91, vcc
	v_cmp_eq_u32_e32 vcc, 0, v83
	s_nop 1
	v_cndmask_b32_e32 v83, v96, v89, vcc
	v_cndmask_b32_e32 v96, v97, v86, vcc
	v_cmp_eq_u32_e32 vcc, 0, v94
	v_cvt_f32_f64_e32 v86, v[92:93]
	s_nop 0
	v_cndmask_b32_e32 v94, v98, v90, vcc
	v_cndmask_b32_e32 v97, v99, v87, vcc
	v_cmp_eq_u32_e32 vcc, 0, v95
	v_cvt_i32_f64_e32 v87, v[100:101]
	v_and_b32_e32 v87, 3, v87
	v_cndmask_b32_e32 v98, v103, v88, vcc
	v_mul_f32_e32 v88, v86, v86
	v_fmamk_f32 v89, v88, 0x3638ef1d, v159
	v_fmaak_f32 v89, v88, v89, 0x3c088888
	v_fmaak_f32 v89, v88, v89, 0xbe2aaaab
	v_fma_f32 v89, v88, v89, 1.0
	v_mul_f32_e32 v86, v89, v86
	v_fmamk_f32 v89, v88, 0xb493f27e, v160
	v_fmaak_f32 v89, v88, v89, 0xbab60b61
	v_fmaak_f32 v89, v88, v89, 0x3d2aaaab
	v_fma_f32 v89, v88, v89, -0.5
	v_cndmask_b32_e32 v95, v102, v91, vcc
	v_fma_f32 v88, v88, v89, 1.0
	v_cmp_eq_u32_e32 vcc, 2, v87
	v_cmp_eq_u32_e64 s[8:9], 1, v87
	s_nop 0
	v_cndmask_b32_e64 v89, v86, -v88, vcc
	v_cndmask_b32_e32 v90, v88, v86, vcc
	v_cndmask_b32_e64 v89, v89, -v86, s[8:9]
	v_cndmask_b32_e64 v90, -v90, v88, s[8:9]
	v_cmp_eq_u32_e32 vcc, 0, v87
	v_mul_f32_e32 v87, v78, v82
	s_mov_b64 s[8:9], 0
	v_cndmask_b32_e32 v92, v89, v88, vcc
	v_cndmask_b32_e32 v93, v90, v86, vcc
	v_mul_f32_e32 v88, v70, v82
	v_mul_f32_e32 v90, v87, v96
	v_mul_f32_e32 v89, v88, v96
	v_fmac_f32_e32 v90, v88, v83
	v_mul_f32_e32 v88, v71, v82
	v_fma_f32 v89, v87, v83, -v89
	v_mul_f32_e32 v87, v79, v82
	v_mul_f32_e32 v91, v88, v97
	v_fma_f32 v91, v87, v94, -v91
	v_mul_f32_e32 v99, v87, v97
	v_mul_f32_e32 v87, v80, v82
	v_fmac_f32_e32 v99, v88, v94
	v_mul_f32_e32 v88, v72, v82
	v_mul_f32_e32 v101, v87, v98
	v_mul_f32_e32 v100, v88, v98
	v_fmac_f32_e32 v101, v88, v95
	v_mul_f32_e32 v88, v73, v82
	v_or_b32_e32 v86, s78, v84
	v_fma_f32 v100, v87, v95, -v100
	v_mul_f32_e32 v87, v81, v82
	v_mul_f32_e32 v102, v88, v93
	v_fma_f32 v102, v87, v92, -v102
	v_mul_f32_e32 v103, v87, v93
	v_mad_u64_u32 v[86:87], s[0:1], v86, s77, v[140:141]
	v_fmac_f32_e32 v103, v88, v92
	v_mad_i32_i24 v87, v85, s77, v87
	v_cvt_pk_bf16_f32 v88, v89, v91
	v_cvt_pk_bf16_f32 v89, v100, v102
	v_cvt_pk_bf16_f32 v90, v90, v99
	v_cvt_pk_bf16_f32 v91, v101, v103
	v_mov_b32_e32 v222, v88
	v_mov_b32_e32 v223, v89
	v_mov_b32_e32 v224, v90
	v_mov_b32_e32 v225, v91
	s_nop 1
	v_permlane16_swap_b32_e32 v222, v224
	v_permlane16_swap_b32_e32 v223, v225
	v_lshl_add_u64 v[228:229], v[86:87], 0, v[226:227]
	global_store_dwordx4 v[228:229], v[222:225], off offset:128
	s_nop 0
	v_mul_f32_e32 v91, v66, v82
	v_mul_f32_e32 v90, v74, v82
	v_mul_f32_e32 v99, v91, v96
	v_fma_f32 v99, v90, v83, -v99
	v_mul_f32_e32 v96, v90, v96
	v_mul_f32_e32 v90, v67, v82
	v_fmac_f32_e32 v96, v91, v83
	v_mul_f32_e32 v83, v75, v82
	v_mul_f32_e32 v91, v90, v97
	v_fma_f32 v100, v83, v94, -v91
	v_mul_f32_e32 v83, v83, v97
	v_fmac_f32_e32 v83, v90, v94
	v_mul_f32_e32 v90, v76, v82
	v_mul_f32_e32 v91, v68, v82
	v_or_b32_e32 v88, s81, v84
	v_mov_b64_e32 v[86:87], s[24:25]
	v_mul_f32_e32 v94, v91, v98
	v_mul_f32_e32 v97, v90, v98
	v_mad_u64_u32 v[88:89], s[0:1], v88, s77, v[86:87]
	v_fma_f32 v94, v90, v95, -v94
	v_fmac_f32_e32 v97, v91, v95
	v_mul_f32_e32 v90, v77, v82
	v_mul_f32_e32 v91, v69, v82
	v_mad_i32_i24 v89, v85, s77, v89
	v_mul_f32_e32 v95, v91, v93
	v_mul_f32_e32 v98, v90, v93
	v_lshl_add_u64 v[86:87], v[88:89], 0, s[26:27]
	v_fma_f32 v95, v90, v92, -v95
	v_fmac_f32_e32 v98, v91, v92
	v_lshl_add_u64 v[90:91], v[88:89], 0, v[134:135]
	v_cvt_pk_bf16_f32 v92, v99, v100
	v_cvt_pk_bf16_f32 v93, v94, v95
	v_cvt_pk_bf16_f32 v88, v96, v83
	v_cvt_pk_bf16_f32 v89, v97, v98
	v_mov_b32_e32 v222, v92
	v_mov_b32_e32 v223, v93
	v_mov_b32_e32 v224, v88
	v_mov_b32_e32 v225, v89
	s_nop 1
	v_permlane16_swap_b32_e32 v222, v224
	v_permlane16_swap_b32_e32 v223, v225
	v_lshl_add_u64 v[228:229], v[90:91], 0, v[226:227]
	global_store_dwordx4 v[228:229], v[222:225], off offset:128
	s_nop 0
.LBB0_634:
	s_andn2_b64 vcc, exec, s[8:9]
	s_cbranch_vccnz .LBB0_636
	v_lshl_add_u64 v[84:85], v[84:85], 0, s[54:55]
	v_mov_b64_e32 v[86:87], s[30:31]
	v_mad_u64_u32 v[86:87], s[0:1], v84, s77, v[86:87]
	v_mad_i32_i24 v87, v85, s77, v87
	v_lshl_add_u64 v[84:85], v[86:87], 0, v[134:135]
	v_pk_mul_f32 v[78:79], v[78:79], v[82:83] op_sel_hi:[1,0]
	v_pk_mul_f32 v[72:73], v[72:73], v[82:83] op_sel_hi:[1,0]
	v_pk_mul_f32 v[70:71], v[70:71], v[82:83] op_sel_hi:[1,0]
	v_pk_mul_f32 v[80:81], v[80:81], v[82:83] op_sel_hi:[1,0]
	v_cvt_pk_bf16_f32 v78, v78, v79
	v_lshl_add_u64 v[86:87], v[86:87], 0, s[40:41]
	v_cvt_pk_bf16_f32 v79, v80, v81
	v_mov_b32_e32 v222, v78
	v_mov_b32_e32 v223, v79
	v_cvt_pk_bf16_f32 v70, v70, v71
	v_cvt_pk_bf16_f32 v71, v72, v73
	v_pk_mul_f32 v[72:73], v[74:75], v[82:83] op_sel_hi:[1,0]
	v_mov_b32_e32 v224, v70
	v_mov_b32_e32 v225, v71
	s_nop 1
	v_permlane16_swap_b32_e32 v222, v224
	v_permlane16_swap_b32_e32 v223, v225
	v_lshl_add_u64 v[228:229], v[84:85], 0, v[226:227]
	global_store_dwordx4 v[228:229], v[222:225], off
	s_nop 0
	v_pk_mul_f32 v[70:71], v[76:77], v[82:83] op_sel_hi:[1,0]
	v_cvt_pk_bf16_f32 v72, v72, v73
	v_pk_mul_f32 v[68:69], v[68:69], v[82:83] op_sel_hi:[1,0]
	v_cvt_pk_bf16_f32 v73, v70, v71
	v_mov_b32_e32 v222, v72
	v_mov_b32_e32 v223, v73
	v_pk_mul_f32 v[66:67], v[66:67], v[82:83] op_sel_hi:[1,0]
	s_nop 0
	v_cvt_pk_bf16_f32 v88, v66, v67
	v_cvt_pk_bf16_f32 v89, v68, v69
	v_mov_b32_e32 v224, v88
	v_mov_b32_e32 v225, v89
	s_nop 1
	v_permlane16_swap_b32_e32 v222, v224
	v_permlane16_swap_b32_e32 v223, v225
	v_lshl_add_u64 v[228:229], v[84:85], 0, v[226:227]
	global_store_dwordx4 v[228:229], v[222:225], off offset:384
	s_nop 0
.LBB0_636:
	v_add_u32_e32 v74, 0x80, v146
	v_lshl_add_u64 v[66:67], v[86:87], 0, v[134:135]
	v_ashrrev_i32_e32 v75, 31, v74
	v_lshlrev_b64 v[66:67], 5, v[74:75]
	v_lshl_add_u64 v[66:67], s[10:11], 0, v[66:67]
	v_mov_b32_e32 v66, v194
	v_mov_b32_e32 v67, v195
	v_mov_b32_e32 v68, v196
	v_mov_b32_e32 v69, v197
	s_and_b64 vcc, exec, s[6:7]
	s_mov_b64 s[8:9], -1
	v_add_f32_e32 v66, v66, v67
	v_add_f32_e32 v67, v68, v69
	v_add_f32_e32 v66, v66, v67
	v_fmamk_f32 v66, v66, 0x3b800000, v158
	v_rsq_f32_e32 v66, v66
	v_lshlrev_b64 v[68:69], 3, v[74:75]
	v_mul_f32_e32 v66, 0x3e16c740, v66
	s_cbranch_vccnz .LBB0_638
	v_mov_b32_e32 v70, v210
	v_mov_b32_e32 v71, v211
	v_mov_b32_e32 v72, v212
	v_mov_b32_e32 v73, v213
	v_and_b32_e32 v67, 0x1fcf, v74
	v_cvt_f32_u32_e32 v67, v67
	v_mul_f32_e32 v70, v70, v67
	v_mul_f32_e32 v74, v71, v67
	v_cvt_f64_f32_e32 v[70:71], v70
	v_mul_f32_e32 v75, v72, v67
	v_mul_f32_e32 v67, v73, v67
	v_cvt_f64_f32_e32 v[72:73], v74
	v_mul_f64 v[78:79], v[70:71], s[42:43]
	v_cvt_f64_f32_e32 v[74:75], v75
	v_mul_f64 v[80:81], v[72:73], s[42:43]
	v_rndne_f64_e32 v[78:79], v[78:79]
	v_mul_f64 v[82:83], v[74:75], s[42:43]
	v_rndne_f64_e32 v[80:81], v[80:81]
	v_fma_f64 v[70:71], v[70:71], s[42:43], -v[78:79]
	v_rndne_f64_e32 v[82:83], v[82:83]
	v_fma_f64 v[72:73], v[72:73], s[42:43], -v[80:81]
	v_mul_f64 v[70:71], v[70:71], s[44:45]
	v_fma_f64 v[74:75], v[74:75], s[42:43], -v[82:83]
	v_mul_f64 v[72:73], v[72:73], s[44:45]
	v_cvt_f32_f64_e32 v70, v[70:71]
	v_mul_f64 v[74:75], v[74:75], s[44:45]
	v_cvt_f32_f64_e32 v71, v[72:73]
	v_mul_f32_e32 v73, v70, v70
	v_cvt_f64_f32_e32 v[76:77], v67
	v_cvt_i32_f64_e32 v67, v[78:79]
	v_cvt_i32_f64_e32 v78, v[80:81]
	v_cvt_f32_f64_e32 v72, v[74:75]
	v_mul_f32_e32 v74, v71, v71
	v_fmamk_f32 v80, v73, 0x3638ef1d, v159
	v_fmamk_f32 v81, v73, 0xb493f27e, v160
	v_cvt_i32_f64_e32 v79, v[82:83]
	v_mul_f32_e32 v75, v72, v72
	v_fmamk_f32 v82, v74, 0x3638ef1d, v159
	v_fmamk_f32 v83, v74, 0xb493f27e, v160
	v_fmaak_f32 v80, v73, v80, 0x3c088888
	v_fmaak_f32 v81, v73, v81, 0xbab60b61
	v_fmamk_f32 v86, v75, 0x3638ef1d, v159
	v_fmamk_f32 v87, v75, 0xb493f27e, v160
	v_fmaak_f32 v82, v74, v82, 0x3c088888
	v_fmaak_f32 v83, v74, v83, 0xbab60b61
	v_fmaak_f32 v80, v73, v80, 0xbe2aaaab
	v_fmaak_f32 v81, v73, v81, 0x3d2aaaab
	v_and_b32_e32 v67, 3, v67
	v_fmaak_f32 v86, v75, v86, 0x3c088888
	v_fmaak_f32 v87, v75, v87, 0xbab60b61
	v_fmaak_f32 v82, v74, v82, 0xbe2aaaab
	v_fmaak_f32 v83, v74, v83, 0x3d2aaaab
	v_fma_f32 v80, v73, v80, 1.0
	v_fma_f32 v81, v73, v81, -0.5
	v_and_b32_e32 v78, 3, v78
	v_fmaak_f32 v86, v75, v86, 0xbe2aaaab
	v_fmaak_f32 v87, v75, v87, 0x3d2aaaab
	v_fma_f32 v82, v74, v82, 1.0
	v_fma_f32 v83, v74, v83, -0.5
	v_mul_f32_e32 v70, v80, v70
	v_fma_f32 v73, v73, v81, 1.0
	v_cmp_eq_u32_e32 vcc, 2, v67
	v_and_b32_e32 v79, 3, v79
	v_fma_f32 v86, v75, v86, 1.0
	v_fma_f32 v87, v75, v87, -0.5
	v_mul_f32_e32 v71, v82, v71
	v_fma_f32 v74, v74, v83, 1.0
	v_cndmask_b32_e64 v80, v70, -v73, vcc
	v_cndmask_b32_e32 v81, v73, v70, vcc
	v_cmp_eq_u32_e32 vcc, 2, v78
	v_mul_f32_e32 v72, v86, v72
	v_fma_f32 v75, v75, v87, 1.0
	v_cndmask_b32_e64 v82, v71, -v74, vcc
	v_cndmask_b32_e32 v83, v74, v71, vcc
	v_cmp_eq_u32_e32 vcc, 2, v79
	v_mul_f64 v[84:85], v[76:77], s[42:43]
	v_rndne_f64_e32 v[84:85], v[84:85]
	v_cndmask_b32_e64 v86, v72, -v75, vcc
	v_cndmask_b32_e32 v87, v75, v72, vcc
	v_cmp_eq_u32_e32 vcc, 1, v67
	v_fma_f64 v[76:77], v[76:77], s[42:43], -v[84:85]
	v_mul_f64 v[76:77], v[76:77], s[44:45]
	v_cndmask_b32_e64 v80, v80, -v70, vcc
	v_cndmask_b32_e64 v81, -v81, v73, vcc
	v_cmp_eq_u32_e32 vcc, 1, v78
	s_nop 1
	v_cndmask_b32_e64 v82, v82, -v71, vcc
	v_cndmask_b32_e64 v83, -v83, v74, vcc
	v_cmp_eq_u32_e32 vcc, 1, v79
	s_nop 1
	v_cndmask_b32_e64 v86, v86, -v72, vcc
	v_cndmask_b32_e64 v87, -v87, v75, vcc
	v_cmp_eq_u32_e32 vcc, 0, v67
	s_nop 1
	v_cndmask_b32_e32 v67, v80, v73, vcc
	v_cndmask_b32_e32 v80, v81, v70, vcc
	v_cmp_eq_u32_e32 vcc, 0, v78
	v_cvt_f32_f64_e32 v70, v[76:77]
	s_nop 0
	v_cndmask_b32_e32 v78, v82, v74, vcc
	v_cndmask_b32_e32 v81, v83, v71, vcc
	v_cmp_eq_u32_e32 vcc, 0, v79
	v_cvt_i32_f64_e32 v71, v[84:85]
	v_and_b32_e32 v71, 3, v71
	v_cndmask_b32_e32 v82, v87, v72, vcc
	v_mul_f32_e32 v72, v70, v70
	v_fmamk_f32 v73, v72, 0x3638ef1d, v159
	v_fmaak_f32 v73, v72, v73, 0x3c088888
	v_fmaak_f32 v73, v72, v73, 0xbe2aaaab
	v_fma_f32 v73, v72, v73, 1.0
	v_mul_f32_e32 v70, v73, v70
	v_fmamk_f32 v73, v72, 0xb493f27e, v160
	v_fmaak_f32 v73, v72, v73, 0xbab60b61
	v_fmaak_f32 v73, v72, v73, 0x3d2aaaab
	v_fma_f32 v73, v72, v73, -0.5
	v_cndmask_b32_e32 v79, v86, v75, vcc
	v_fma_f32 v72, v72, v73, 1.0
	v_cmp_eq_u32_e32 vcc, 2, v71
	v_cmp_eq_u32_e64 s[8:9], 1, v71
	s_nop 0
	v_cndmask_b32_e64 v73, v70, -v72, vcc
	v_cndmask_b32_e32 v74, v72, v70, vcc
	v_cndmask_b32_e64 v73, v73, -v70, s[8:9]
	v_cndmask_b32_e64 v74, -v74, v72, s[8:9]
	v_cmp_eq_u32_e32 vcc, 0, v71
	v_mul_f32_e32 v71, v62, v66
	s_mov_b64 s[8:9], 0
	v_cndmask_b32_e32 v76, v73, v72, vcc
	v_cndmask_b32_e32 v77, v74, v70, vcc
	v_mul_f32_e32 v72, v54, v66
	v_mul_f32_e32 v74, v71, v80
	v_mul_f32_e32 v73, v72, v80
	v_fmac_f32_e32 v74, v72, v67
	v_mul_f32_e32 v72, v55, v66
	v_fma_f32 v73, v71, v67, -v73
	v_mul_f32_e32 v71, v63, v66
	v_mul_f32_e32 v75, v72, v81
	v_fma_f32 v75, v71, v78, -v75
	v_mul_f32_e32 v83, v71, v81
	v_mul_f32_e32 v71, v64, v66
	v_fmac_f32_e32 v83, v72, v78
	v_mul_f32_e32 v72, v56, v66
	v_mul_f32_e32 v85, v71, v82
	v_mul_f32_e32 v84, v72, v82
	v_fmac_f32_e32 v85, v72, v79
	v_mul_f32_e32 v72, v57, v66
	v_or_b32_e32 v70, s78, v68
	v_fma_f32 v84, v71, v79, -v84
	v_mul_f32_e32 v71, v65, v66
	v_mul_f32_e32 v86, v72, v77
	v_fma_f32 v86, v71, v76, -v86
	v_mul_f32_e32 v87, v71, v77
	v_mad_u64_u32 v[70:71], s[0:1], v70, s77, v[140:141]
	v_fmac_f32_e32 v87, v72, v76
	v_mad_i32_i24 v71, v69, s77, v71
	v_cvt_pk_bf16_f32 v72, v73, v75
	v_cvt_pk_bf16_f32 v73, v84, v86
	v_cvt_pk_bf16_f32 v74, v74, v83
	v_cvt_pk_bf16_f32 v75, v85, v87
	v_mov_b32_e32 v222, v72
	v_mov_b32_e32 v223, v73
	v_mov_b32_e32 v224, v74
	v_mov_b32_e32 v225, v75
	s_nop 1
	v_permlane16_swap_b32_e32 v222, v224
	v_permlane16_swap_b32_e32 v223, v225
	v_lshl_add_u64 v[228:229], v[70:71], 0, v[226:227]
	global_store_dwordx4 v[228:229], v[222:225], off offset:128
	s_nop 0
	v_mul_f32_e32 v75, v50, v66
	v_mul_f32_e32 v74, v58, v66
	v_mul_f32_e32 v83, v75, v80
	v_fma_f32 v83, v74, v67, -v83
	v_mul_f32_e32 v80, v74, v80
	v_mul_f32_e32 v74, v51, v66
	v_fmac_f32_e32 v80, v75, v67
	v_mul_f32_e32 v67, v59, v66
	v_mul_f32_e32 v75, v74, v81
	v_fma_f32 v84, v67, v78, -v75
	v_mul_f32_e32 v67, v67, v81
	v_fmac_f32_e32 v67, v74, v78
	v_mul_f32_e32 v74, v60, v66
	v_mul_f32_e32 v75, v52, v66
	v_or_b32_e32 v72, s81, v68
	v_mov_b64_e32 v[70:71], s[24:25]
	v_mul_f32_e32 v78, v75, v82
	v_mul_f32_e32 v81, v74, v82
	v_mad_u64_u32 v[72:73], s[0:1], v72, s77, v[70:71]
	v_fma_f32 v78, v74, v79, -v78
	v_fmac_f32_e32 v81, v75, v79
	v_mul_f32_e32 v74, v61, v66
	v_mul_f32_e32 v75, v53, v66
	v_mad_i32_i24 v73, v69, s77, v73
	v_mul_f32_e32 v79, v75, v77
	v_mul_f32_e32 v82, v74, v77
	v_lshl_add_u64 v[70:71], v[72:73], 0, s[26:27]
	v_fma_f32 v79, v74, v76, -v79
	v_fmac_f32_e32 v82, v75, v76
	v_lshl_add_u64 v[74:75], v[72:73], 0, v[134:135]
	v_cvt_pk_bf16_f32 v76, v83, v84
	v_cvt_pk_bf16_f32 v77, v78, v79
	v_cvt_pk_bf16_f32 v72, v80, v67
	v_cvt_pk_bf16_f32 v73, v81, v82
	v_mov_b32_e32 v222, v76
	v_mov_b32_e32 v223, v77
	v_mov_b32_e32 v224, v72
	v_mov_b32_e32 v225, v73
	s_nop 1
	v_permlane16_swap_b32_e32 v222, v224
	v_permlane16_swap_b32_e32 v223, v225
	v_lshl_add_u64 v[228:229], v[74:75], 0, v[226:227]
	global_store_dwordx4 v[228:229], v[222:225], off offset:128
	s_nop 0
.LBB0_638:
	s_andn2_b64 vcc, exec, s[8:9]
	s_cbranch_vccnz .LBB0_640
	v_lshl_add_u64 v[68:69], v[68:69], 0, s[54:55]
	v_mov_b64_e32 v[70:71], s[30:31]
	v_mad_u64_u32 v[70:71], s[0:1], v68, s77, v[70:71]
	v_mad_i32_i24 v71, v69, s77, v71
	v_lshl_add_u64 v[68:69], v[70:71], 0, v[134:135]
	v_pk_mul_f32 v[62:63], v[62:63], v[66:67] op_sel_hi:[1,0]
	v_pk_mul_f32 v[56:57], v[56:57], v[66:67] op_sel_hi:[1,0]
	v_pk_mul_f32 v[54:55], v[54:55], v[66:67] op_sel_hi:[1,0]
	v_pk_mul_f32 v[64:65], v[64:65], v[66:67] op_sel_hi:[1,0]
	v_cvt_pk_bf16_f32 v62, v62, v63
	v_lshl_add_u64 v[70:71], v[70:71], 0, s[40:41]
	v_cvt_pk_bf16_f32 v63, v64, v65
	v_mov_b32_e32 v222, v62
	v_mov_b32_e32 v223, v63
	v_cvt_pk_bf16_f32 v54, v54, v55
	v_cvt_pk_bf16_f32 v55, v56, v57
	v_pk_mul_f32 v[56:57], v[58:59], v[66:67] op_sel_hi:[1,0]
	v_mov_b32_e32 v224, v54
	v_mov_b32_e32 v225, v55
	s_nop 1
	v_permlane16_swap_b32_e32 v222, v224
	v_permlane16_swap_b32_e32 v223, v225
	v_lshl_add_u64 v[228:229], v[68:69], 0, v[226:227]
	global_store_dwordx4 v[228:229], v[222:225], off
	s_nop 0
	v_pk_mul_f32 v[54:55], v[60:61], v[66:67] op_sel_hi:[1,0]
	v_cvt_pk_bf16_f32 v56, v56, v57
	v_pk_mul_f32 v[52:53], v[52:53], v[66:67] op_sel_hi:[1,0]
	v_cvt_pk_bf16_f32 v57, v54, v55
	v_mov_b32_e32 v222, v56
	v_mov_b32_e32 v223, v57
	v_pk_mul_f32 v[50:51], v[50:51], v[66:67] op_sel_hi:[1,0]
	s_nop 0
	v_cvt_pk_bf16_f32 v72, v50, v51
	v_cvt_pk_bf16_f32 v73, v52, v53
	v_mov_b32_e32 v224, v72
	v_mov_b32_e32 v225, v73
	s_nop 1
	v_permlane16_swap_b32_e32 v222, v224
	v_permlane16_swap_b32_e32 v223, v225
	v_lshl_add_u64 v[228:229], v[68:69], 0, v[226:227]
	global_store_dwordx4 v[228:229], v[222:225], off offset:384
	s_nop 0
.LBB0_640:
	v_add_u32_e32 v58, 0x90, v146
	v_lshl_add_u64 v[50:51], v[70:71], 0, v[134:135]
	v_ashrrev_i32_e32 v59, 31, v58
	v_lshlrev_b64 v[50:51], 5, v[58:59]
	v_lshl_add_u64 v[50:51], s[10:11], 0, v[50:51]
	v_mov_b32_e32 v50, v198
	v_mov_b32_e32 v51, v199
	v_mov_b32_e32 v52, v200
	v_mov_b32_e32 v53, v201
	s_and_b64 vcc, exec, s[6:7]
	s_mov_b64 s[8:9], -1
	v_add_f32_e32 v50, v50, v51
	v_add_f32_e32 v51, v52, v53
	v_add_f32_e32 v50, v50, v51
	v_fmamk_f32 v50, v50, 0x3b800000, v158
	v_rsq_f32_e32 v50, v50
	v_lshlrev_b64 v[52:53], 3, v[58:59]
	v_mul_f32_e32 v50, 0x3e16c740, v50
	s_cbranch_vccnz .LBB0_642
	v_mov_b32_e32 v54, v210
	v_mov_b32_e32 v55, v211
	v_mov_b32_e32 v56, v212
	v_mov_b32_e32 v57, v213
	v_and_b32_e32 v51, 0x1fdf, v58
	v_cvt_f32_u32_e32 v51, v51
	v_mul_f32_e32 v54, v54, v51
	v_mul_f32_e32 v58, v55, v51
	v_cvt_f64_f32_e32 v[54:55], v54
	v_mul_f32_e32 v59, v56, v51
	v_mul_f32_e32 v51, v57, v51
	v_cvt_f64_f32_e32 v[56:57], v58
	v_mul_f64 v[62:63], v[54:55], s[42:43]
	v_cvt_f64_f32_e32 v[58:59], v59
	v_mul_f64 v[64:65], v[56:57], s[42:43]
	v_rndne_f64_e32 v[62:63], v[62:63]
	v_mul_f64 v[66:67], v[58:59], s[42:43]
	v_rndne_f64_e32 v[64:65], v[64:65]
	v_fma_f64 v[54:55], v[54:55], s[42:43], -v[62:63]
	v_rndne_f64_e32 v[66:67], v[66:67]
	v_fma_f64 v[56:57], v[56:57], s[42:43], -v[64:65]
	v_mul_f64 v[54:55], v[54:55], s[44:45]
	v_fma_f64 v[58:59], v[58:59], s[42:43], -v[66:67]
	v_mul_f64 v[56:57], v[56:57], s[44:45]
	v_cvt_f32_f64_e32 v54, v[54:55]
	v_mul_f64 v[58:59], v[58:59], s[44:45]
	v_cvt_f32_f64_e32 v55, v[56:57]
	v_mul_f32_e32 v57, v54, v54
	v_cvt_f64_f32_e32 v[60:61], v51
	v_cvt_i32_f64_e32 v51, v[62:63]
	v_cvt_i32_f64_e32 v62, v[64:65]
	v_cvt_f32_f64_e32 v56, v[58:59]
	v_mul_f32_e32 v58, v55, v55
	v_fmamk_f32 v64, v57, 0x3638ef1d, v159
	v_fmamk_f32 v65, v57, 0xb493f27e, v160
	v_cvt_i32_f64_e32 v63, v[66:67]
	v_mul_f32_e32 v59, v56, v56
	v_fmamk_f32 v66, v58, 0x3638ef1d, v159
	v_fmamk_f32 v67, v58, 0xb493f27e, v160
	v_fmaak_f32 v64, v57, v64, 0x3c088888
	v_fmaak_f32 v65, v57, v65, 0xbab60b61
	v_fmamk_f32 v70, v59, 0x3638ef1d, v159
	v_fmamk_f32 v71, v59, 0xb493f27e, v160
	v_fmaak_f32 v66, v58, v66, 0x3c088888
	v_fmaak_f32 v67, v58, v67, 0xbab60b61
	v_fmaak_f32 v64, v57, v64, 0xbe2aaaab
	v_fmaak_f32 v65, v57, v65, 0x3d2aaaab
	v_and_b32_e32 v51, 3, v51
	v_fmaak_f32 v70, v59, v70, 0x3c088888
	v_fmaak_f32 v71, v59, v71, 0xbab60b61
	v_fmaak_f32 v66, v58, v66, 0xbe2aaaab
	v_fmaak_f32 v67, v58, v67, 0x3d2aaaab
	v_fma_f32 v64, v57, v64, 1.0
	v_fma_f32 v65, v57, v65, -0.5
	v_and_b32_e32 v62, 3, v62
	v_fmaak_f32 v70, v59, v70, 0xbe2aaaab
	v_fmaak_f32 v71, v59, v71, 0x3d2aaaab
	v_fma_f32 v66, v58, v66, 1.0
	v_fma_f32 v67, v58, v67, -0.5
	v_mul_f32_e32 v54, v64, v54
	v_fma_f32 v57, v57, v65, 1.0
	v_cmp_eq_u32_e32 vcc, 2, v51
	v_and_b32_e32 v63, 3, v63
	v_fma_f32 v70, v59, v70, 1.0
	v_fma_f32 v71, v59, v71, -0.5
	v_mul_f32_e32 v55, v66, v55
	v_fma_f32 v58, v58, v67, 1.0
	v_cndmask_b32_e64 v64, v54, -v57, vcc
	v_cndmask_b32_e32 v65, v57, v54, vcc
	v_cmp_eq_u32_e32 vcc, 2, v62
	v_mul_f32_e32 v56, v70, v56
	v_fma_f32 v59, v59, v71, 1.0
	v_cndmask_b32_e64 v66, v55, -v58, vcc
	v_cndmask_b32_e32 v67, v58, v55, vcc
	v_cmp_eq_u32_e32 vcc, 2, v63
	v_mul_f64 v[68:69], v[60:61], s[42:43]
	v_rndne_f64_e32 v[68:69], v[68:69]
	v_cndmask_b32_e64 v70, v56, -v59, vcc
	v_cndmask_b32_e32 v71, v59, v56, vcc
	v_cmp_eq_u32_e32 vcc, 1, v51
	v_fma_f64 v[60:61], v[60:61], s[42:43], -v[68:69]
	v_mul_f64 v[60:61], v[60:61], s[44:45]
	v_cndmask_b32_e64 v64, v64, -v54, vcc
	v_cndmask_b32_e64 v65, -v65, v57, vcc
	v_cmp_eq_u32_e32 vcc, 1, v62
	s_nop 1
	v_cndmask_b32_e64 v66, v66, -v55, vcc
	v_cndmask_b32_e64 v67, -v67, v58, vcc
	v_cmp_eq_u32_e32 vcc, 1, v63
	s_nop 1
	v_cndmask_b32_e64 v70, v70, -v56, vcc
	v_cndmask_b32_e64 v71, -v71, v59, vcc
	v_cmp_eq_u32_e32 vcc, 0, v51
	s_nop 1
	v_cndmask_b32_e32 v51, v64, v57, vcc
	v_cndmask_b32_e32 v64, v65, v54, vcc
	v_cmp_eq_u32_e32 vcc, 0, v62
	v_cvt_f32_f64_e32 v54, v[60:61]
	s_nop 0
	v_cndmask_b32_e32 v62, v66, v58, vcc
	v_cndmask_b32_e32 v65, v67, v55, vcc
	v_cmp_eq_u32_e32 vcc, 0, v63
	v_cvt_i32_f64_e32 v55, v[68:69]
	v_and_b32_e32 v55, 3, v55
	v_cndmask_b32_e32 v66, v71, v56, vcc
	v_mul_f32_e32 v56, v54, v54
	v_fmamk_f32 v57, v56, 0x3638ef1d, v159
	v_fmaak_f32 v57, v56, v57, 0x3c088888
	v_fmaak_f32 v57, v56, v57, 0xbe2aaaab
	v_fma_f32 v57, v56, v57, 1.0
	v_mul_f32_e32 v54, v57, v54
	v_fmamk_f32 v57, v56, 0xb493f27e, v160
	v_fmaak_f32 v57, v56, v57, 0xbab60b61
	v_fmaak_f32 v57, v56, v57, 0x3d2aaaab
	v_fma_f32 v57, v56, v57, -0.5
	v_cndmask_b32_e32 v63, v70, v59, vcc
	v_fma_f32 v56, v56, v57, 1.0
	v_cmp_eq_u32_e32 vcc, 2, v55
	v_cmp_eq_u32_e64 s[8:9], 1, v55
	s_nop 0
	v_cndmask_b32_e64 v57, v54, -v56, vcc
	v_cndmask_b32_e32 v58, v56, v54, vcc
	v_cndmask_b32_e64 v57, v57, -v54, s[8:9]
	v_cndmask_b32_e64 v58, -v58, v56, s[8:9]
	v_cmp_eq_u32_e32 vcc, 0, v55
	v_mul_f32_e32 v55, v46, v50
	s_mov_b64 s[8:9], 0
	v_cndmask_b32_e32 v60, v57, v56, vcc
	v_cndmask_b32_e32 v61, v58, v54, vcc
	v_mul_f32_e32 v56, v38, v50
	v_mul_f32_e32 v58, v55, v64
	v_mul_f32_e32 v57, v56, v64
	v_fmac_f32_e32 v58, v56, v51
	v_mul_f32_e32 v56, v39, v50
	v_fma_f32 v57, v55, v51, -v57
	v_mul_f32_e32 v55, v47, v50
	v_mul_f32_e32 v59, v56, v65
	v_fma_f32 v59, v55, v62, -v59
	v_mul_f32_e32 v67, v55, v65
	v_mul_f32_e32 v55, v48, v50
	v_fmac_f32_e32 v67, v56, v62
	v_mul_f32_e32 v56, v40, v50
	v_mul_f32_e32 v69, v55, v66
	v_mul_f32_e32 v68, v56, v66
	v_fmac_f32_e32 v69, v56, v63
	v_mul_f32_e32 v56, v41, v50
	v_or_b32_e32 v54, s78, v52
	v_fma_f32 v68, v55, v63, -v68
	v_mul_f32_e32 v55, v49, v50
	v_mul_f32_e32 v70, v56, v61
	v_fma_f32 v70, v55, v60, -v70
	v_mul_f32_e32 v71, v55, v61
	v_mad_u64_u32 v[54:55], s[0:1], v54, s77, v[140:141]
	v_fmac_f32_e32 v71, v56, v60
	v_mad_i32_i24 v55, v53, s77, v55
	v_cvt_pk_bf16_f32 v56, v57, v59
	v_cvt_pk_bf16_f32 v57, v68, v70
	v_cvt_pk_bf16_f32 v58, v58, v67
	v_cvt_pk_bf16_f32 v59, v69, v71
	v_mov_b32_e32 v222, v56
	v_mov_b32_e32 v223, v57
	v_mov_b32_e32 v224, v58
	v_mov_b32_e32 v225, v59
	s_nop 1
	v_permlane16_swap_b32_e32 v222, v224
	v_permlane16_swap_b32_e32 v223, v225
	v_lshl_add_u64 v[228:229], v[54:55], 0, v[226:227]
	global_store_dwordx4 v[228:229], v[222:225], off offset:128
	s_nop 0
	v_mul_f32_e32 v59, v34, v50
	v_mul_f32_e32 v58, v42, v50
	v_mul_f32_e32 v67, v59, v64
	v_fma_f32 v67, v58, v51, -v67
	v_mul_f32_e32 v64, v58, v64
	v_mul_f32_e32 v58, v35, v50
	v_fmac_f32_e32 v64, v59, v51
	v_mul_f32_e32 v51, v43, v50
	v_mul_f32_e32 v59, v58, v65
	v_fma_f32 v68, v51, v62, -v59
	v_mul_f32_e32 v51, v51, v65
	v_fmac_f32_e32 v51, v58, v62
	v_mul_f32_e32 v58, v44, v50
	v_mul_f32_e32 v59, v36, v50
	v_or_b32_e32 v56, s81, v52
	v_mov_b64_e32 v[54:55], s[24:25]
	v_mul_f32_e32 v62, v59, v66
	v_mul_f32_e32 v65, v58, v66
	v_mad_u64_u32 v[56:57], s[0:1], v56, s77, v[54:55]
	v_fma_f32 v62, v58, v63, -v62
	v_fmac_f32_e32 v65, v59, v63
	v_mul_f32_e32 v58, v45, v50
	v_mul_f32_e32 v59, v37, v50
	v_mad_i32_i24 v57, v53, s77, v57
	v_mul_f32_e32 v63, v59, v61
	v_mul_f32_e32 v66, v58, v61
	v_lshl_add_u64 v[54:55], v[56:57], 0, s[26:27]
	v_fma_f32 v63, v58, v60, -v63
	v_fmac_f32_e32 v66, v59, v60
	v_lshl_add_u64 v[58:59], v[56:57], 0, v[134:135]
	v_cvt_pk_bf16_f32 v60, v67, v68
	v_cvt_pk_bf16_f32 v61, v62, v63
	v_cvt_pk_bf16_f32 v56, v64, v51
	v_cvt_pk_bf16_f32 v57, v65, v66
	v_mov_b32_e32 v222, v60
	v_mov_b32_e32 v223, v61
	v_mov_b32_e32 v224, v56
	v_mov_b32_e32 v225, v57
	s_nop 1
	v_permlane16_swap_b32_e32 v222, v224
	v_permlane16_swap_b32_e32 v223, v225
	v_lshl_add_u64 v[228:229], v[58:59], 0, v[226:227]
	global_store_dwordx4 v[228:229], v[222:225], off offset:128
	s_nop 0
.LBB0_642:
	s_andn2_b64 vcc, exec, s[8:9]
	s_cbranch_vccnz .LBB0_644
	v_lshl_add_u64 v[52:53], v[52:53], 0, s[54:55]
	v_mov_b64_e32 v[54:55], s[30:31]
	v_mad_u64_u32 v[54:55], s[0:1], v52, s77, v[54:55]
	v_mad_i32_i24 v55, v53, s77, v55
	v_lshl_add_u64 v[52:53], v[54:55], 0, v[134:135]
	v_pk_mul_f32 v[46:47], v[46:47], v[50:51] op_sel_hi:[1,0]
	v_pk_mul_f32 v[40:41], v[40:41], v[50:51] op_sel_hi:[1,0]
	v_pk_mul_f32 v[38:39], v[38:39], v[50:51] op_sel_hi:[1,0]
	v_pk_mul_f32 v[48:49], v[48:49], v[50:51] op_sel_hi:[1,0]
	v_cvt_pk_bf16_f32 v46, v46, v47
	v_lshl_add_u64 v[54:55], v[54:55], 0, s[40:41]
	v_cvt_pk_bf16_f32 v47, v48, v49
	v_mov_b32_e32 v222, v46
	v_mov_b32_e32 v223, v47
	v_cvt_pk_bf16_f32 v38, v38, v39
	v_cvt_pk_bf16_f32 v39, v40, v41
	v_pk_mul_f32 v[40:41], v[42:43], v[50:51] op_sel_hi:[1,0]
	v_mov_b32_e32 v224, v38
	v_mov_b32_e32 v225, v39
	s_nop 1
	v_permlane16_swap_b32_e32 v222, v224
	v_permlane16_swap_b32_e32 v223, v225
	v_lshl_add_u64 v[228:229], v[52:53], 0, v[226:227]
	global_store_dwordx4 v[228:229], v[222:225], off
	s_nop 0
	v_pk_mul_f32 v[38:39], v[44:45], v[50:51] op_sel_hi:[1,0]
	v_cvt_pk_bf16_f32 v40, v40, v41
	v_pk_mul_f32 v[36:37], v[36:37], v[50:51] op_sel_hi:[1,0]
	v_cvt_pk_bf16_f32 v41, v38, v39
	v_mov_b32_e32 v222, v40
	v_mov_b32_e32 v223, v41
	v_pk_mul_f32 v[34:35], v[34:35], v[50:51] op_sel_hi:[1,0]
	s_nop 0
	v_cvt_pk_bf16_f32 v56, v34, v35
	v_cvt_pk_bf16_f32 v57, v36, v37
	v_mov_b32_e32 v224, v56
	v_mov_b32_e32 v225, v57
	s_nop 1
	v_permlane16_swap_b32_e32 v222, v224
	v_permlane16_swap_b32_e32 v223, v225
	v_lshl_add_u64 v[228:229], v[52:53], 0, v[226:227]
	global_store_dwordx4 v[228:229], v[222:225], off offset:384
	s_nop 0
.LBB0_644:
	v_add_u32_e32 v42, 0xa0, v146
	v_lshl_add_u64 v[34:35], v[54:55], 0, v[134:135]
	v_ashrrev_i32_e32 v43, 31, v42
	v_lshlrev_b64 v[34:35], 5, v[42:43]
	v_lshl_add_u64 v[34:35], s[10:11], 0, v[34:35]
	v_mov_b32_e32 v34, v202
	v_mov_b32_e32 v35, v203
	v_mov_b32_e32 v36, v204
	v_mov_b32_e32 v37, v205
	s_and_b64 vcc, exec, s[6:7]
	s_mov_b64 s[8:9], -1
	v_add_f32_e32 v34, v34, v35
	v_add_f32_e32 v35, v36, v37
	v_add_f32_e32 v34, v34, v35
	v_fmamk_f32 v34, v34, 0x3b800000, v158
	v_rsq_f32_e32 v34, v34
	v_lshlrev_b64 v[36:37], 3, v[42:43]
	v_mul_f32_e32 v34, 0x3e16c740, v34
	s_cbranch_vccnz .LBB0_646
	v_mov_b32_e32 v38, v210
	v_mov_b32_e32 v39, v211
	v_mov_b32_e32 v40, v212
	v_mov_b32_e32 v41, v213
	v_and_b32_e32 v35, 0x1fef, v42
	v_cvt_f32_u32_e32 v35, v35
	v_mul_f32_e32 v38, v38, v35
	v_mul_f32_e32 v42, v39, v35
	v_cvt_f64_f32_e32 v[38:39], v38
	v_mul_f32_e32 v43, v40, v35
	v_mul_f32_e32 v35, v41, v35
	v_cvt_f64_f32_e32 v[40:41], v42
	v_mul_f64 v[46:47], v[38:39], s[42:43]
	v_cvt_f64_f32_e32 v[42:43], v43
	v_mul_f64 v[48:49], v[40:41], s[42:43]
	v_rndne_f64_e32 v[46:47], v[46:47]
	v_mul_f64 v[50:51], v[42:43], s[42:43]
	v_rndne_f64_e32 v[48:49], v[48:49]
	v_fma_f64 v[38:39], v[38:39], s[42:43], -v[46:47]
	v_rndne_f64_e32 v[50:51], v[50:51]
	v_fma_f64 v[40:41], v[40:41], s[42:43], -v[48:49]
	v_mul_f64 v[38:39], v[38:39], s[44:45]
	v_fma_f64 v[42:43], v[42:43], s[42:43], -v[50:51]
	v_mul_f64 v[40:41], v[40:41], s[44:45]
	v_cvt_f32_f64_e32 v38, v[38:39]
	v_mul_f64 v[42:43], v[42:43], s[44:45]
	v_cvt_f32_f64_e32 v39, v[40:41]
	v_mul_f32_e32 v41, v38, v38
	v_cvt_f64_f32_e32 v[44:45], v35
	v_cvt_i32_f64_e32 v35, v[46:47]
	v_cvt_i32_f64_e32 v46, v[48:49]
	v_cvt_f32_f64_e32 v40, v[42:43]
	v_mul_f32_e32 v42, v39, v39
	v_fmamk_f32 v48, v41, 0x3638ef1d, v159
	v_fmamk_f32 v49, v41, 0xb493f27e, v160
	v_cvt_i32_f64_e32 v47, v[50:51]
	v_mul_f32_e32 v43, v40, v40
	v_fmamk_f32 v50, v42, 0x3638ef1d, v159
	v_fmamk_f32 v51, v42, 0xb493f27e, v160
	v_fmaak_f32 v48, v41, v48, 0x3c088888
	v_fmaak_f32 v49, v41, v49, 0xbab60b61
	v_fmamk_f32 v54, v43, 0x3638ef1d, v159
	v_fmamk_f32 v55, v43, 0xb493f27e, v160
	v_fmaak_f32 v50, v42, v50, 0x3c088888
	v_fmaak_f32 v51, v42, v51, 0xbab60b61
	v_fmaak_f32 v48, v41, v48, 0xbe2aaaab
	v_fmaak_f32 v49, v41, v49, 0x3d2aaaab
	v_and_b32_e32 v35, 3, v35
	v_fmaak_f32 v54, v43, v54, 0x3c088888
	v_fmaak_f32 v55, v43, v55, 0xbab60b61
	v_fmaak_f32 v50, v42, v50, 0xbe2aaaab
	v_fmaak_f32 v51, v42, v51, 0x3d2aaaab
	v_fma_f32 v48, v41, v48, 1.0
	v_fma_f32 v49, v41, v49, -0.5
	v_and_b32_e32 v46, 3, v46
	v_fmaak_f32 v54, v43, v54, 0xbe2aaaab
	v_fmaak_f32 v55, v43, v55, 0x3d2aaaab
	v_fma_f32 v50, v42, v50, 1.0
	v_fma_f32 v51, v42, v51, -0.5
	v_mul_f32_e32 v38, v48, v38
	v_fma_f32 v41, v41, v49, 1.0
	v_cmp_eq_u32_e32 vcc, 2, v35
	v_and_b32_e32 v47, 3, v47
	v_fma_f32 v54, v43, v54, 1.0
	v_fma_f32 v55, v43, v55, -0.5
	v_mul_f32_e32 v39, v50, v39
	v_fma_f32 v42, v42, v51, 1.0
	v_cndmask_b32_e64 v48, v38, -v41, vcc
	v_cndmask_b32_e32 v49, v41, v38, vcc
	v_cmp_eq_u32_e32 vcc, 2, v46
	v_mul_f32_e32 v40, v54, v40
	v_fma_f32 v43, v43, v55, 1.0
	v_cndmask_b32_e64 v50, v39, -v42, vcc
	v_cndmask_b32_e32 v51, v42, v39, vcc
	v_cmp_eq_u32_e32 vcc, 2, v47
	v_mul_f64 v[52:53], v[44:45], s[42:43]
	v_rndne_f64_e32 v[52:53], v[52:53]
	v_cndmask_b32_e64 v54, v40, -v43, vcc
	v_cndmask_b32_e32 v55, v43, v40, vcc
	v_cmp_eq_u32_e32 vcc, 1, v35
	v_fma_f64 v[44:45], v[44:45], s[42:43], -v[52:53]
	v_mul_f64 v[44:45], v[44:45], s[44:45]
	v_cndmask_b32_e64 v48, v48, -v38, vcc
	v_cndmask_b32_e64 v49, -v49, v41, vcc
	v_cmp_eq_u32_e32 vcc, 1, v46
	s_nop 1
	v_cndmask_b32_e64 v50, v50, -v39, vcc
	v_cndmask_b32_e64 v51, -v51, v42, vcc
	v_cmp_eq_u32_e32 vcc, 1, v47
	s_nop 1
	v_cndmask_b32_e64 v54, v54, -v40, vcc
	v_cndmask_b32_e64 v55, -v55, v43, vcc
	v_cmp_eq_u32_e32 vcc, 0, v35
	s_nop 1
	v_cndmask_b32_e32 v35, v48, v41, vcc
	v_cndmask_b32_e32 v48, v49, v38, vcc
	v_cmp_eq_u32_e32 vcc, 0, v46
	v_cvt_f32_f64_e32 v38, v[44:45]
	s_nop 0
	v_cndmask_b32_e32 v46, v50, v42, vcc
	v_cndmask_b32_e32 v49, v51, v39, vcc
	v_cmp_eq_u32_e32 vcc, 0, v47
	v_cvt_i32_f64_e32 v39, v[52:53]
	v_and_b32_e32 v39, 3, v39
	v_cndmask_b32_e32 v50, v55, v40, vcc
	v_mul_f32_e32 v40, v38, v38
	v_fmamk_f32 v41, v40, 0x3638ef1d, v159
	v_fmaak_f32 v41, v40, v41, 0x3c088888
	v_fmaak_f32 v41, v40, v41, 0xbe2aaaab
	v_fma_f32 v41, v40, v41, 1.0
	v_mul_f32_e32 v38, v41, v38
	v_fmamk_f32 v41, v40, 0xb493f27e, v160
	v_fmaak_f32 v41, v40, v41, 0xbab60b61
	v_fmaak_f32 v41, v40, v41, 0x3d2aaaab
	v_fma_f32 v41, v40, v41, -0.5
	v_cndmask_b32_e32 v47, v54, v43, vcc
	v_fma_f32 v40, v40, v41, 1.0
	v_cmp_eq_u32_e32 vcc, 2, v39
	v_cmp_eq_u32_e64 s[8:9], 1, v39
	s_nop 0
	v_cndmask_b32_e64 v41, v38, -v40, vcc
	v_cndmask_b32_e32 v42, v40, v38, vcc
	v_cndmask_b32_e64 v41, v41, -v38, s[8:9]
	v_cndmask_b32_e64 v42, -v42, v40, s[8:9]
	v_cmp_eq_u32_e32 vcc, 0, v39
	v_mul_f32_e32 v39, v30, v34
	s_mov_b64 s[8:9], 0
	v_cndmask_b32_e32 v44, v41, v40, vcc
	v_cndmask_b32_e32 v45, v42, v38, vcc
	v_mul_f32_e32 v40, v22, v34
	v_mul_f32_e32 v42, v39, v48
	v_mul_f32_e32 v41, v40, v48
	v_fmac_f32_e32 v42, v40, v35
	v_mul_f32_e32 v40, v23, v34
	v_fma_f32 v41, v39, v35, -v41
	v_mul_f32_e32 v39, v31, v34
	v_mul_f32_e32 v43, v40, v49
	v_fma_f32 v43, v39, v46, -v43
	v_mul_f32_e32 v51, v39, v49
	v_mul_f32_e32 v39, v32, v34
	v_fmac_f32_e32 v51, v40, v46
	v_mul_f32_e32 v40, v24, v34
	v_mul_f32_e32 v53, v39, v50
	v_mul_f32_e32 v52, v40, v50
	v_fmac_f32_e32 v53, v40, v47
	v_mul_f32_e32 v40, v25, v34
	v_or_b32_e32 v38, s78, v36
	v_fma_f32 v52, v39, v47, -v52
	v_mul_f32_e32 v39, v33, v34
	v_mul_f32_e32 v54, v40, v45
	v_fma_f32 v54, v39, v44, -v54
	v_mul_f32_e32 v55, v39, v45
	v_mad_u64_u32 v[38:39], s[0:1], v38, s77, v[140:141]
	v_fmac_f32_e32 v55, v40, v44
	v_mad_i32_i24 v39, v37, s77, v39
	v_cvt_pk_bf16_f32 v40, v41, v43
	v_cvt_pk_bf16_f32 v41, v52, v54
	v_cvt_pk_bf16_f32 v42, v42, v51
	v_cvt_pk_bf16_f32 v43, v53, v55
	v_mov_b32_e32 v222, v40
	v_mov_b32_e32 v223, v41
	v_mov_b32_e32 v224, v42
	v_mov_b32_e32 v225, v43
	s_nop 1
	v_permlane16_swap_b32_e32 v222, v224
	v_permlane16_swap_b32_e32 v223, v225
	v_lshl_add_u64 v[228:229], v[38:39], 0, v[226:227]
	global_store_dwordx4 v[228:229], v[222:225], off offset:128
	s_nop 0
	v_mul_f32_e32 v43, v18, v34
	v_mul_f32_e32 v42, v26, v34
	v_mul_f32_e32 v51, v43, v48
	v_fma_f32 v51, v42, v35, -v51
	v_mul_f32_e32 v48, v42, v48
	v_mul_f32_e32 v42, v19, v34
	v_fmac_f32_e32 v48, v43, v35
	v_mul_f32_e32 v35, v27, v34
	v_mul_f32_e32 v43, v42, v49
	v_fma_f32 v52, v35, v46, -v43
	v_mul_f32_e32 v35, v35, v49
	v_fmac_f32_e32 v35, v42, v46
	v_mul_f32_e32 v42, v28, v34
	v_mul_f32_e32 v43, v20, v34
	v_or_b32_e32 v40, s81, v36
	v_mov_b64_e32 v[38:39], s[24:25]
	v_mul_f32_e32 v46, v43, v50
	v_mul_f32_e32 v49, v42, v50
	v_mad_u64_u32 v[40:41], s[0:1], v40, s77, v[38:39]
	v_fma_f32 v46, v42, v47, -v46
	v_fmac_f32_e32 v49, v43, v47
	v_mul_f32_e32 v42, v29, v34
	v_mul_f32_e32 v43, v21, v34
	v_mad_i32_i24 v41, v37, s77, v41
	v_mul_f32_e32 v47, v43, v45
	v_mul_f32_e32 v50, v42, v45
	v_lshl_add_u64 v[38:39], v[40:41], 0, s[26:27]
	v_fma_f32 v47, v42, v44, -v47
	v_fmac_f32_e32 v50, v43, v44
	v_lshl_add_u64 v[42:43], v[40:41], 0, v[134:135]
	v_cvt_pk_bf16_f32 v44, v51, v52
	v_cvt_pk_bf16_f32 v45, v46, v47
	v_cvt_pk_bf16_f32 v40, v48, v35
	v_cvt_pk_bf16_f32 v41, v49, v50
	v_mov_b32_e32 v222, v44
	v_mov_b32_e32 v223, v45
	v_mov_b32_e32 v224, v40
	v_mov_b32_e32 v225, v41
	s_nop 1
	v_permlane16_swap_b32_e32 v222, v224
	v_permlane16_swap_b32_e32 v223, v225
	v_lshl_add_u64 v[228:229], v[42:43], 0, v[226:227]
	global_store_dwordx4 v[228:229], v[222:225], off offset:128
	s_nop 0
.LBB0_646:
	s_andn2_b64 vcc, exec, s[8:9]
	s_cbranch_vccnz .LBB0_648
	v_lshl_add_u64 v[36:37], v[36:37], 0, s[54:55]
	v_mov_b64_e32 v[38:39], s[30:31]
	v_mad_u64_u32 v[38:39], s[0:1], v36, s77, v[38:39]
	v_mad_i32_i24 v39, v37, s77, v39
	v_lshl_add_u64 v[36:37], v[38:39], 0, v[134:135]
	v_pk_mul_f32 v[30:31], v[30:31], v[34:35] op_sel_hi:[1,0]
	v_pk_mul_f32 v[24:25], v[24:25], v[34:35] op_sel_hi:[1,0]
	v_pk_mul_f32 v[22:23], v[22:23], v[34:35] op_sel_hi:[1,0]
	v_pk_mul_f32 v[32:33], v[32:33], v[34:35] op_sel_hi:[1,0]
	v_cvt_pk_bf16_f32 v30, v30, v31
	v_lshl_add_u64 v[38:39], v[38:39], 0, s[40:41]
	v_cvt_pk_bf16_f32 v31, v32, v33
	v_mov_b32_e32 v222, v30
	v_mov_b32_e32 v223, v31
	v_cvt_pk_bf16_f32 v22, v22, v23
	v_cvt_pk_bf16_f32 v23, v24, v25
	v_pk_mul_f32 v[24:25], v[26:27], v[34:35] op_sel_hi:[1,0]
	v_mov_b32_e32 v224, v22
	v_mov_b32_e32 v225, v23
	s_nop 1
	v_permlane16_swap_b32_e32 v222, v224
	v_permlane16_swap_b32_e32 v223, v225
	v_lshl_add_u64 v[228:229], v[36:37], 0, v[226:227]
	global_store_dwordx4 v[228:229], v[222:225], off
	s_nop 0
	v_pk_mul_f32 v[22:23], v[28:29], v[34:35] op_sel_hi:[1,0]
	v_cvt_pk_bf16_f32 v24, v24, v25
	v_pk_mul_f32 v[20:21], v[20:21], v[34:35] op_sel_hi:[1,0]
	v_cvt_pk_bf16_f32 v25, v22, v23
	v_mov_b32_e32 v222, v24
	v_mov_b32_e32 v223, v25
	v_pk_mul_f32 v[18:19], v[18:19], v[34:35] op_sel_hi:[1,0]
	s_nop 0
	v_cvt_pk_bf16_f32 v40, v18, v19
	v_cvt_pk_bf16_f32 v41, v20, v21
	v_mov_b32_e32 v224, v40
	v_mov_b32_e32 v225, v41
	s_nop 1
	v_permlane16_swap_b32_e32 v222, v224
	v_permlane16_swap_b32_e32 v223, v225
	v_lshl_add_u64 v[228:229], v[36:37], 0, v[226:227]
	global_store_dwordx4 v[228:229], v[222:225], off offset:384
	s_nop 0
.LBB0_648:
	v_add_u32_e32 v26, 0xb0, v146
	v_lshl_add_u64 v[18:19], v[38:39], 0, v[134:135]
	v_ashrrev_i32_e32 v27, 31, v26
	v_lshlrev_b64 v[18:19], 5, v[26:27]
	v_lshl_add_u64 v[18:19], s[10:11], 0, v[18:19]
	v_mov_b32_e32 v18, v206
	v_mov_b32_e32 v19, v207
	v_mov_b32_e32 v20, v208
	v_mov_b32_e32 v21, v209
	s_and_b64 vcc, exec, s[6:7]
	s_mov_b64 s[6:7], -1
	v_add_f32_e32 v18, v18, v19
	v_add_f32_e32 v19, v20, v21
	v_add_f32_e32 v18, v18, v19
	v_fmamk_f32 v18, v18, 0x3b800000, v158
	v_rsq_f32_e32 v18, v18
	v_lshlrev_b64 v[20:21], 3, v[26:27]
	v_mul_f32_e32 v18, 0x3e16c740, v18
	s_cbranch_vccnz .LBB0_650
	v_mov_b32_e32 v22, v210
	v_mov_b32_e32 v23, v211
	v_mov_b32_e32 v24, v212
	v_mov_b32_e32 v25, v213
	v_and_b32_e32 v19, 0x1fff, v26
	v_cvt_f32_u32_e32 v19, v19
	v_mul_f32_e32 v22, v22, v19
	v_mul_f32_e32 v26, v23, v19
	v_cvt_f64_f32_e32 v[22:23], v22
	v_mul_f32_e32 v27, v24, v19
	v_mul_f32_e32 v19, v25, v19
	v_cvt_f64_f32_e32 v[24:25], v26
	v_mul_f64 v[30:31], v[22:23], s[42:43]
	v_cvt_f64_f32_e32 v[26:27], v27
	v_mul_f64 v[32:33], v[24:25], s[42:43]
	v_rndne_f64_e32 v[30:31], v[30:31]
	v_mul_f64 v[34:35], v[26:27], s[42:43]
	v_rndne_f64_e32 v[32:33], v[32:33]
	v_fma_f64 v[22:23], v[22:23], s[42:43], -v[30:31]
	v_rndne_f64_e32 v[34:35], v[34:35]
	v_fma_f64 v[24:25], v[24:25], s[42:43], -v[32:33]
	v_mul_f64 v[22:23], v[22:23], s[44:45]
	v_fma_f64 v[26:27], v[26:27], s[42:43], -v[34:35]
	v_mul_f64 v[24:25], v[24:25], s[44:45]
	v_cvt_f32_f64_e32 v22, v[22:23]
	v_mul_f64 v[26:27], v[26:27], s[44:45]
	v_cvt_f32_f64_e32 v23, v[24:25]
	v_mul_f32_e32 v25, v22, v22
	v_cvt_f64_f32_e32 v[28:29], v19
	v_cvt_i32_f64_e32 v19, v[30:31]
	v_cvt_i32_f64_e32 v30, v[32:33]
	v_cvt_f32_f64_e32 v24, v[26:27]
	v_mul_f32_e32 v26, v23, v23
	v_fmamk_f32 v32, v25, 0x3638ef1d, v159
	v_fmamk_f32 v33, v25, 0xb493f27e, v160
	v_cvt_i32_f64_e32 v31, v[34:35]
	v_mul_f32_e32 v27, v24, v24
	v_fmamk_f32 v34, v26, 0x3638ef1d, v159
	v_fmamk_f32 v35, v26, 0xb493f27e, v160
	v_fmaak_f32 v32, v25, v32, 0x3c088888
	v_fmaak_f32 v33, v25, v33, 0xbab60b61
	v_fmamk_f32 v38, v27, 0x3638ef1d, v159
	v_fmamk_f32 v39, v27, 0xb493f27e, v160
	v_fmaak_f32 v34, v26, v34, 0x3c088888
	v_fmaak_f32 v35, v26, v35, 0xbab60b61
	v_fmaak_f32 v32, v25, v32, 0xbe2aaaab
	v_fmaak_f32 v33, v25, v33, 0x3d2aaaab
	v_and_b32_e32 v19, 3, v19
	v_fmaak_f32 v38, v27, v38, 0x3c088888
	v_fmaak_f32 v39, v27, v39, 0xbab60b61
	v_fmaak_f32 v34, v26, v34, 0xbe2aaaab
	v_fmaak_f32 v35, v26, v35, 0x3d2aaaab
	v_fma_f32 v32, v25, v32, 1.0
	v_fma_f32 v33, v25, v33, -0.5
	v_and_b32_e32 v30, 3, v30
	v_fmaak_f32 v38, v27, v38, 0xbe2aaaab
	v_fmaak_f32 v39, v27, v39, 0x3d2aaaab
	v_fma_f32 v34, v26, v34, 1.0
	v_fma_f32 v35, v26, v35, -0.5
	v_mul_f32_e32 v22, v32, v22
	v_fma_f32 v25, v25, v33, 1.0
	v_cmp_eq_u32_e32 vcc, 2, v19
	v_and_b32_e32 v31, 3, v31
	v_fma_f32 v38, v27, v38, 1.0
	v_fma_f32 v39, v27, v39, -0.5
	v_mul_f32_e32 v23, v34, v23
	v_fma_f32 v26, v26, v35, 1.0
	v_cndmask_b32_e64 v32, v22, -v25, vcc
	v_cndmask_b32_e32 v33, v25, v22, vcc
	v_cmp_eq_u32_e32 vcc, 2, v30
	v_mul_f32_e32 v24, v38, v24
	v_fma_f32 v27, v27, v39, 1.0
	v_cndmask_b32_e64 v34, v23, -v26, vcc
	v_cndmask_b32_e32 v35, v26, v23, vcc
	v_cmp_eq_u32_e32 vcc, 2, v31
	v_mul_f64 v[36:37], v[28:29], s[42:43]
	v_rndne_f64_e32 v[36:37], v[36:37]
	v_cndmask_b32_e64 v38, v24, -v27, vcc
	v_cndmask_b32_e32 v39, v27, v24, vcc
	v_cmp_eq_u32_e32 vcc, 1, v19
	v_fma_f64 v[28:29], v[28:29], s[42:43], -v[36:37]
	v_mul_f64 v[28:29], v[28:29], s[44:45]
	v_cndmask_b32_e64 v32, v32, -v22, vcc
	v_cndmask_b32_e64 v33, -v33, v25, vcc
	v_cmp_eq_u32_e32 vcc, 1, v30
	s_nop 1
	v_cndmask_b32_e64 v34, v34, -v23, vcc
	v_cndmask_b32_e64 v35, -v35, v26, vcc
	v_cmp_eq_u32_e32 vcc, 1, v31
	s_nop 1
	v_cndmask_b32_e64 v38, v38, -v24, vcc
	v_cndmask_b32_e64 v39, -v39, v27, vcc
	v_cmp_eq_u32_e32 vcc, 0, v19
	s_nop 1
	v_cndmask_b32_e32 v19, v32, v25, vcc
	v_cndmask_b32_e32 v32, v33, v22, vcc
	v_cmp_eq_u32_e32 vcc, 0, v30
	v_cvt_f32_f64_e32 v22, v[28:29]
	s_nop 0
	v_cndmask_b32_e32 v30, v34, v26, vcc
	v_cndmask_b32_e32 v33, v35, v23, vcc
	v_cmp_eq_u32_e32 vcc, 0, v31
	v_cvt_i32_f64_e32 v23, v[36:37]
	v_and_b32_e32 v23, 3, v23
	v_cndmask_b32_e32 v34, v39, v24, vcc
	v_mul_f32_e32 v24, v22, v22
	v_fmamk_f32 v25, v24, 0x3638ef1d, v159
	v_fmaak_f32 v25, v24, v25, 0x3c088888
	v_fmaak_f32 v25, v24, v25, 0xbe2aaaab
	v_fma_f32 v25, v24, v25, 1.0
	v_mul_f32_e32 v22, v25, v22
	v_fmamk_f32 v25, v24, 0xb493f27e, v160
	v_fmaak_f32 v25, v24, v25, 0xbab60b61
	v_fmaak_f32 v25, v24, v25, 0x3d2aaaab
	v_fma_f32 v25, v24, v25, -0.5
	v_cndmask_b32_e32 v31, v38, v27, vcc
	v_fma_f32 v24, v24, v25, 1.0
	v_cmp_eq_u32_e32 vcc, 2, v23
	v_cmp_eq_u32_e64 s[6:7], 1, v23
	s_nop 0
	v_cndmask_b32_e64 v25, v22, -v24, vcc
	v_cndmask_b32_e32 v26, v24, v22, vcc
	v_cndmask_b32_e64 v25, v25, -v22, s[6:7]
	v_cndmask_b32_e64 v26, -v26, v24, s[6:7]
	v_cmp_eq_u32_e32 vcc, 0, v23
	v_mul_f32_e32 v23, v14, v18
	s_mov_b64 s[6:7], 0
	v_cndmask_b32_e32 v28, v25, v24, vcc
	v_cndmask_b32_e32 v29, v26, v22, vcc
	v_mul_f32_e32 v24, v6, v18
	v_mul_f32_e32 v26, v23, v32
	v_mul_f32_e32 v25, v24, v32
	v_fmac_f32_e32 v26, v24, v19
	v_mul_f32_e32 v24, v7, v18
	v_fma_f32 v25, v23, v19, -v25
	v_mul_f32_e32 v23, v15, v18
	v_mul_f32_e32 v27, v24, v33
	v_fma_f32 v27, v23, v30, -v27
	v_mul_f32_e32 v35, v23, v33
	v_mul_f32_e32 v23, v16, v18
	v_fmac_f32_e32 v35, v24, v30
	v_mul_f32_e32 v24, v8, v18
	v_mul_f32_e32 v37, v23, v34
	v_mul_f32_e32 v36, v24, v34
	v_fmac_f32_e32 v37, v24, v31
	v_mul_f32_e32 v24, v9, v18
	v_or_b32_e32 v22, s78, v20
	v_fma_f32 v36, v23, v31, -v36
	v_mul_f32_e32 v23, v17, v18
	v_mul_f32_e32 v38, v24, v29
	v_fma_f32 v38, v23, v28, -v38
	v_mul_f32_e32 v39, v23, v29
	v_mad_u64_u32 v[22:23], s[0:1], v22, s77, v[140:141]
	v_fmac_f32_e32 v39, v24, v28
	v_mad_i32_i24 v23, v21, s77, v23
	v_cvt_pk_bf16_f32 v24, v25, v27
	v_cvt_pk_bf16_f32 v25, v36, v38
	v_cvt_pk_bf16_f32 v26, v26, v35
	v_cvt_pk_bf16_f32 v27, v37, v39
	v_mov_b32_e32 v222, v24
	v_mov_b32_e32 v223, v25
	v_mov_b32_e32 v224, v26
	v_mov_b32_e32 v225, v27
	s_nop 1
	v_permlane16_swap_b32_e32 v222, v224
	v_permlane16_swap_b32_e32 v223, v225
	v_lshl_add_u64 v[228:229], v[22:23], 0, v[226:227]
	global_store_dwordx4 v[228:229], v[222:225], off offset:128
	s_nop 0
	v_mul_f32_e32 v27, v2, v18
	v_mul_f32_e32 v26, v10, v18
	v_mul_f32_e32 v35, v27, v32
	v_fma_f32 v35, v26, v19, -v35
	v_mul_f32_e32 v32, v26, v32
	v_mul_f32_e32 v26, v3, v18
	v_fmac_f32_e32 v32, v27, v19
	v_mul_f32_e32 v19, v11, v18
	v_mul_f32_e32 v27, v26, v33
	v_fma_f32 v36, v19, v30, -v27
	v_mul_f32_e32 v19, v19, v33
	v_fmac_f32_e32 v19, v26, v30
	v_mul_f32_e32 v26, v12, v18
	v_mul_f32_e32 v27, v4, v18
	v_or_b32_e32 v24, s81, v20
	v_mov_b64_e32 v[22:23], s[24:25]
	v_mul_f32_e32 v30, v27, v34
	v_mul_f32_e32 v33, v26, v34
	v_mad_u64_u32 v[24:25], s[0:1], v24, s77, v[22:23]
	v_fma_f32 v30, v26, v31, -v30
	v_fmac_f32_e32 v33, v27, v31
	v_mul_f32_e32 v26, v13, v18
	v_mul_f32_e32 v27, v5, v18
	v_mad_i32_i24 v25, v21, s77, v25
	v_mul_f32_e32 v31, v27, v29
	v_mul_f32_e32 v34, v26, v29
	v_lshl_add_u64 v[22:23], v[24:25], 0, s[26:27]
	v_fma_f32 v31, v26, v28, -v31
	v_fmac_f32_e32 v34, v27, v28
	v_lshl_add_u64 v[26:27], v[24:25], 0, v[134:135]
	v_cvt_pk_bf16_f32 v28, v35, v36
	v_cvt_pk_bf16_f32 v29, v30, v31
	v_cvt_pk_bf16_f32 v24, v32, v19
	v_cvt_pk_bf16_f32 v25, v33, v34
	v_mov_b32_e32 v222, v28
	v_mov_b32_e32 v223, v29
	v_mov_b32_e32 v224, v24
	v_mov_b32_e32 v225, v25
	s_nop 1
	v_permlane16_swap_b32_e32 v222, v224
	v_permlane16_swap_b32_e32 v223, v225
	v_lshl_add_u64 v[228:229], v[26:27], 0, v[226:227]
	global_store_dwordx4 v[228:229], v[222:225], off offset:128
	s_nop 0
.LBB0_650:
	s_andn2_b64 vcc, exec, s[6:7]
	s_cbranch_vccnz .LBB0_652
	v_lshl_add_u64 v[20:21], v[20:21], 0, s[54:55]
	v_mov_b64_e32 v[22:23], s[30:31]
	v_mad_u64_u32 v[22:23], s[0:1], v20, s77, v[22:23]
	v_mad_i32_i24 v23, v21, s77, v23
	v_lshl_add_u64 v[20:21], v[22:23], 0, v[134:135]
	v_pk_mul_f32 v[14:15], v[14:15], v[18:19] op_sel_hi:[1,0]
	v_pk_mul_f32 v[8:9], v[8:9], v[18:19] op_sel_hi:[1,0]
	v_pk_mul_f32 v[6:7], v[6:7], v[18:19] op_sel_hi:[1,0]
	v_pk_mul_f32 v[16:17], v[16:17], v[18:19] op_sel_hi:[1,0]
	v_cvt_pk_bf16_f32 v14, v14, v15
	v_lshl_add_u64 v[22:23], v[22:23], 0, s[40:41]
	v_cvt_pk_bf16_f32 v15, v16, v17
	v_mov_b32_e32 v222, v14
	v_mov_b32_e32 v223, v15
	v_cvt_pk_bf16_f32 v6, v6, v7
	v_cvt_pk_bf16_f32 v7, v8, v9
	v_pk_mul_f32 v[8:9], v[10:11], v[18:19] op_sel_hi:[1,0]
	v_mov_b32_e32 v224, v6
	v_mov_b32_e32 v225, v7
	s_nop 1
	v_permlane16_swap_b32_e32 v222, v224
	v_permlane16_swap_b32_e32 v223, v225
	v_lshl_add_u64 v[228:229], v[20:21], 0, v[226:227]
	global_store_dwordx4 v[228:229], v[222:225], off
	s_nop 0
	v_pk_mul_f32 v[6:7], v[12:13], v[18:19] op_sel_hi:[1,0]
	v_cvt_pk_bf16_f32 v8, v8, v9
	v_pk_mul_f32 v[4:5], v[4:5], v[18:19] op_sel_hi:[1,0]
	v_cvt_pk_bf16_f32 v9, v6, v7
	v_mov_b32_e32 v222, v8
	v_mov_b32_e32 v223, v9
	v_pk_mul_f32 v[2:3], v[2:3], v[18:19] op_sel_hi:[1,0]
	s_nop 0
	v_cvt_pk_bf16_f32 v24, v2, v3
	v_cvt_pk_bf16_f32 v25, v4, v5
	v_mov_b32_e32 v224, v24
	v_mov_b32_e32 v225, v25
	s_nop 1
	v_permlane16_swap_b32_e32 v222, v224
	v_permlane16_swap_b32_e32 v223, v225
	v_lshl_add_u64 v[228:229], v[20:21], 0, v[226:227]
	global_store_dwordx4 v[228:229], v[222:225], off offset:384
	s_nop 0
.LBB0_652:
	v_lshl_add_u64 v[2:3], v[22:23], 0, v[134:135]
	s_andn2_b64 vcc, exec, s[4:5]
	s_mov_b64 s[4:5], -1
	s_cbranch_vccnz .LBB0_615
	s_andn2_b64 vcc, exec, s[14:15]
	s_cbranch_vccnz .LBB0_614
	s_barrier
	s_branch .LBB0_614
